# GEMM tile loops: wave priority raised to 3 while the 8 LDS-DMA loads of a k-tile are issued (on top of the back-to-back DMA issue)
# speedup vs baseline: 1.0132x; 1.0109x over previous
; __device__ __forceinline__ void gemm_mainloop_d(const bf16_t* __restrict__ Ap, int lda, const bf16_t* __restrict__ Bt, int K,
;                                                 int m0, int n0, f32x4 (&acc)[4][4], char* lds) {
;     ...
;   auto dma = [&](int kt, int st) {
;     char* la = lds + st * 32768; char* lb = la + 16384;
; #pragma unroll
;     for (int i = 0; i < 4; i++) {
;       const int row = i * 32 + lrow; const int c = cph ^ ((row >> 1) & 7);
;       __builtin_amdgcn_global_load_lds((const unsigned*)(Ap + (size_t)(m0 + row) * lda + kt * 64 + c * 8), (__attribute__((address_space(3))) unsigned*)(la + i * 4096 + tid * 16), 16, 0, 0);
;       __builtin_amdgcn_global_load_lds((const unsigned*)(Bt + (size_t)(n0 + row) * K + kt * 64 + c * 8), (__attribute__((address_space(3))) unsigned*)(lb + i * 4096 + tid * 16), 16, 0, 0);
;     }
;   };
;   dma(0, 0);
;   asm volatile("s_waitcnt vmcnt(0)" ::: "memory"); __builtin_amdgcn_s_barrier(); asm volatile("" ::: "memory");
;   for (int kt = 0; kt < nk; kt++) {
;     const int st = kt & 1;
;     if (kt + 1 < nk) dma(kt + 1, st ^ 1);
;     const char* la = lds + st * 32768; const char* lb = la + 16384;
;     bf16x8 af[2][4], bfv[2][4];
; #pragma unroll
;     for (int kc = 0; kc < 2; kc++) {
; #pragma unroll
;       for (int m = 0; m < 4; m++) { const int row = wr * 64 + m * 16 + fr; af[kc][m] = *(const bf16x8*)(la + (row * 8 + ((kc * 4 + fq) ^ ((row >> 1) & 7))) * 16); }
; #pragma unroll
;       for (int n = 0; n < 4; n++) { const int row = wc * 64 + n * 16 + fr; bfv[kc][n] = *(const bf16x8*)(lb + (row * 8 + ((kc * 4 + fq) ^ ((row >> 1) & 7))) * 16); }
;     }
;     __builtin_amdgcn_s_setprio(1);
; #pragma unroll
;     for (int kc = 0; kc < 2; kc++)
; #pragma unroll
;       for (int m = 0; m < 4; m++)
; #pragma unroll
;         for (int n = 0; n < 4; n++) acc[m][n] = __builtin_amdgcn_mfma_f32_16x16x32_bf16(bfv[kc][n], af[kc][m], acc[m][n], 0, 0, 0);
;     __builtin_amdgcn_s_setprio(0);
;     asm volatile("s_waitcnt vmcnt(0) lgkmcnt(0)" ::: "memory"); __builtin_amdgcn_s_barrier(); asm volatile("" ::: "memory");
;   }
.LBB0_95:
	s_setprio 3
	s_and_b32 s29, s26, 0x8000
	s_xor_b32 s37, s29, 0x8000
	s_add_i32 s37, s37, vcc_hi
	s_mov_b32 m0, s37
	s_add_i32 vcc_lo, s37, 0x4000
	global_load_lds_dwordx4 v150, s[46:47]
	s_mov_b32 m0, vcc_lo
	s_add_i32 vcc_lo, s37, 0x1000
	global_load_lds_dwordx4 v151, s[46:47]
	s_mov_b32 m0, vcc_lo
	s_add_i32 vcc_lo, s37, 0x5000
	global_load_lds_dwordx4 v152, s[46:47]
	s_mov_b32 m0, vcc_lo
	s_add_i32 vcc_lo, s37, 0x2000
	global_load_lds_dwordx4 v153, s[46:47]
	s_mov_b32 m0, vcc_lo
	s_add_i32 vcc_lo, s37, 0x6000
	global_load_lds_dwordx4 v154, s[46:47]
	s_mov_b32 m0, vcc_lo
	s_add_i32 vcc_lo, s37, 0x3000
	global_load_lds_dwordx4 v155, s[46:47]
	s_mov_b32 m0, vcc_lo
	s_add_i32 vcc_lo, s37, 0x7000
	global_load_lds_dwordx4 v156, s[46:47]
	s_mov_b32 m0, vcc_lo
	s_nop 0
	global_load_lds_dwordx4 v157, s[46:47]
	s_setprio 0
	v_add_u32_e32 v150, 0x80, v150
	v_add_u32_e32 v151, 0x80, v151
	v_add_u32_e32 v152, 0x80, v152
	v_add_u32_e32 v153, 0x80, v153
	v_add_u32_e32 v154, 0x80, v154
	v_add_u32_e32 v155, 0x80, v155
	v_add_u32_e32 v156, 0x80, v156
	v_add_u32_e32 v157, 0x80, v157
	v_add_u32_e32 v98, s29, v85
	v_add_u32_e32 v114, s29, v84
	v_add_u32_e32 v130, s29, v83
	v_add_u32_e32 v146, s29, v2
	ds_read_b128 v[86:89], v98
	ds_read_b128 v[90:93], v98 offset:2048
	ds_read_b128 v[94:97], v98 offset:4096
	ds_read_b128 v[98:101], v98 offset:6144
	ds_read_b128 v[102:105], v114 offset:16384
	ds_read_b128 v[106:109], v114 offset:18432
	ds_read_b128 v[110:113], v114 offset:20480
	ds_read_b128 v[114:117], v114 offset:22528
	ds_read_b128 v[118:121], v130
	ds_read_b128 v[122:125], v130 offset:2048
	ds_read_b128 v[126:129], v130 offset:4096
	ds_read_b128 v[130:133], v130 offset:6144
	ds_read_b128 v[134:137], v146 offset:16384
	ds_read_b128 v[138:141], v146 offset:18432
	ds_read_b128 v[142:145], v146 offset:20480
	ds_read_b128 v[146:149], v146 offset:22528
	s_setprio 1
	s_waitcnt lgkmcnt(0)
	v_mfma_f32_16x16x32_bf16 v[64:67], v[102:105], v[86:89], v[64:67]
	v_mfma_f32_16x16x32_bf16 v[60:63], v[106:109], v[86:89], v[60:63]
	v_mfma_f32_16x16x32_bf16 v[56:59], v[110:113], v[86:89], v[56:59]
	v_mfma_f32_16x16x32_bf16 v[52:55], v[114:117], v[86:89], v[52:55]
	v_mfma_f32_16x16x32_bf16 v[48:51], v[102:105], v[90:93], v[48:51]
	v_mfma_f32_16x16x32_bf16 v[44:47], v[106:109], v[90:93], v[44:47]
	v_mfma_f32_16x16x32_bf16 v[40:43], v[110:113], v[90:93], v[40:43]
	v_mfma_f32_16x16x32_bf16 v[36:39], v[114:117], v[90:93], v[36:39]
	v_mfma_f32_16x16x32_bf16 v[32:35], v[102:105], v[94:97], v[32:35]
	v_mfma_f32_16x16x32_bf16 v[28:31], v[106:109], v[94:97], v[28:31]
	v_mfma_f32_16x16x32_bf16 v[24:27], v[110:113], v[94:97], v[24:27]
	v_mfma_f32_16x16x32_bf16 v[20:23], v[114:117], v[94:97], v[20:23]
	v_mfma_f32_16x16x32_bf16 v[16:19], v[102:105], v[98:101], v[16:19]
	v_mfma_f32_16x16x32_bf16 v[12:15], v[106:109], v[98:101], v[12:15]
	v_mfma_f32_16x16x32_bf16 v[8:11], v[110:113], v[98:101], v[8:11]
	v_mfma_f32_16x16x32_bf16 v[4:7], v[114:117], v[98:101], v[4:7]
	v_mfma_f32_16x16x32_bf16 v[64:67], v[134:137], v[118:121], v[64:67]
	v_mfma_f32_16x16x32_bf16 v[60:63], v[138:141], v[118:121], v[60:63]
	v_mfma_f32_16x16x32_bf16 v[56:59], v[142:145], v[118:121], v[56:59]
	v_mfma_f32_16x16x32_bf16 v[52:55], v[146:149], v[118:121], v[52:55]
	v_mfma_f32_16x16x32_bf16 v[48:51], v[134:137], v[122:125], v[48:51]
	v_mfma_f32_16x16x32_bf16 v[44:47], v[138:141], v[122:125], v[44:47]
	v_mfma_f32_16x16x32_bf16 v[40:43], v[142:145], v[122:125], v[40:43]
	v_mfma_f32_16x16x32_bf16 v[36:39], v[146:149], v[122:125], v[36:39]
	v_mfma_f32_16x16x32_bf16 v[32:35], v[134:137], v[126:129], v[32:35]
	v_mfma_f32_16x16x32_bf16 v[28:31], v[138:141], v[126:129], v[28:31]
	v_mfma_f32_16x16x32_bf16 v[24:27], v[142:145], v[126:129], v[24:27]
	v_mfma_f32_16x16x32_bf16 v[20:23], v[146:149], v[126:129], v[20:23]
	v_mfma_f32_16x16x32_bf16 v[16:19], v[134:137], v[130:133], v[16:19]
	v_mfma_f32_16x16x32_bf16 v[12:15], v[138:141], v[130:133], v[12:15]
	v_mfma_f32_16x16x32_bf16 v[8:11], v[142:145], v[130:133], v[8:11]
	v_mfma_f32_16x16x32_bf16 v[4:7], v[146:149], v[130:133], v[4:7]
	s_setprio 0
	s_waitcnt vmcnt(0) lgkmcnt(0)
	s_barrier
	s_add_u32 s24, s24, 0x80
	s_addc_u32 s25, s25, 0
	s_add_i32 s26, s26, 0x8000
	s_cmpk_eq_i32 s24, 0x1580
	s_cbranch_scc0 .LBB0_95
; __device__ __forceinline__ void gemm_mainloop_d(const bf16_t* __restrict__ Ap, int lda, const bf16_t* __restrict__ Bt, int K,
;                                                 int m0, int n0, f32x4 (&acc)[4][4], char* lds) {
;     ...
;     const char* la = lds + st * 32768; const char* lb = la + 16384;
;     bf16x8 af[2][4], bfv[2][4];
; #pragma unroll
;     for (int kc = 0; kc < 2; kc++) {
; #pragma unroll
;       for (int m = 0; m < 4; m++) { const int row = wr * 64 + m * 16 + fr; af[kc][m] = *(const bf16x8*)(la + (row * 8 + ((kc * 4 + fq) ^ ((row >> 1) & 7))) * 16); }
; #pragma unroll
;       for (int n = 0; n < 4; n++) { const int row = wc * 64 + n * 16 + fr; bfv[kc][n] = *(const bf16x8*)(lb + (row * 8 + ((kc * 4 + fq) ^ ((row >> 1) & 7))) * 16); }
;     }
;     __builtin_amdgcn_s_setprio(1);
; #pragma unroll
;     for (int kc = 0; kc < 2; kc++)
; #pragma unroll
;       for (int m = 0; m < 4; m++)
; #pragma unroll
;         for (int n = 0; n < 4; n++) acc[m][n] = __builtin_amdgcn_mfma_f32_16x16x32_bf16(bfv[kc][n], af[kc][m], acc[m][n], 0, 0, 0);
;     __builtin_amdgcn_s_setprio(0);
;     asm volatile("s_waitcnt vmcnt(0) lgkmcnt(0)" ::: "memory"); __builtin_amdgcn_s_barrier(); asm volatile("" ::: "memory");
;   }
	v_add_u32_e32 v0, 0, v85
	ds_read_b128 v[68:71], v0 offset:32768
	ds_read_b128 v[72:75], v0 offset:34816
	ds_read_b128 v[76:79], v0 offset:36864
	ds_read_b128 v[86:89], v0 offset:38912
	v_add_u32_e32 v0, 0, v84
	ds_read_b128 v[90:93], v0 offset:49152
	ds_read_b128 v[94:97], v0 offset:51200
	ds_read_b128 v[98:101], v0 offset:53248
	ds_read_b128 v[102:105], v0 offset:55296
	v_add_u32_e32 v0, 0, v83
	s_add_u32 s24, s46, s27
	ds_read_b128 v[80:83], v0 offset:32768
	ds_read_b128 v[106:109], v0 offset:34816
	ds_read_b128 v[110:113], v0 offset:36864
	ds_read_b128 v[114:117], v0 offset:38912
	v_add_u32_e32 v0, 0, v2
	s_addc_u32 s25, s47, 0
	ds_read_b128 v[118:121], v0 offset:49152
	ds_read_b128 v[122:125], v0 offset:51200
	ds_read_b128 v[126:129], v0 offset:53248
	ds_read_b128 v[130:133], v0 offset:55296
	s_add_u32 s28, s46, s28
	s_addc_u32 s29, s47, 0
	s_add_u32 s26, s24, 0x65a8000
	s_addc_u32 s27, s25, 0
	s_add_u32 s24, s28, 0xff8c000
	s_addc_u32 s25, s29, 0
	s_setprio 1
	s_waitcnt lgkmcnt(0)
	v_mfma_f32_16x16x32_bf16 v[56:59], v[98:101], v[68:71], v[56:59]
	v_mfma_f32_16x16x32_bf16 v[48:51], v[90:93], v[72:75], v[48:51]
	v_mfma_f32_16x16x32_bf16 v[44:47], v[94:97], v[72:75], v[44:47]
	v_mfma_f32_16x16x32_bf16 v[40:43], v[98:101], v[72:75], v[40:43]
	v_mfma_f32_16x16x32_bf16 v[36:39], v[102:105], v[72:75], v[36:39]
	v_mfma_f32_16x16x32_bf16 v[32:35], v[90:93], v[76:79], v[32:35]
	v_mfma_f32_16x16x32_bf16 v[28:31], v[94:97], v[76:79], v[28:31]
	v_mfma_f32_16x16x32_bf16 v[24:27], v[98:101], v[76:79], v[24:27]
	v_mfma_f32_16x16x32_bf16 v[20:23], v[102:105], v[76:79], v[20:23]
	v_mfma_f32_16x16x32_bf16 v[16:19], v[90:93], v[86:89], v[16:19]
	v_mfma_f32_16x16x32_bf16 v[12:15], v[94:97], v[86:89], v[12:15]
	v_mfma_f32_16x16x32_bf16 v[8:11], v[98:101], v[86:89], v[8:11]
	v_mfma_f32_16x16x32_bf16 v[4:7], v[102:105], v[86:89], v[4:7]
	v_mfma_f32_16x16x32_bf16 v[64:67], v[90:93], v[68:71], v[64:67]
	v_mfma_f32_16x16x32_bf16 v[60:63], v[94:97], v[68:71], v[60:63]
	v_mfma_f32_16x16x32_bf16 v[52:55], v[102:105], v[68:71], v[52:55]
	v_mfma_f32_16x16x32_bf16 v[56:59], v[126:129], v[80:83], v[56:59]
	v_mfma_f32_16x16x32_bf16 v[48:51], v[118:121], v[106:109], v[48:51]
	v_mfma_f32_16x16x32_bf16 v[44:47], v[122:125], v[106:109], v[44:47]
	v_mfma_f32_16x16x32_bf16 v[40:43], v[126:129], v[106:109], v[40:43]
	v_mfma_f32_16x16x32_bf16 v[36:39], v[130:133], v[106:109], v[36:39]
	v_mfma_f32_16x16x32_bf16 v[32:35], v[118:121], v[110:113], v[32:35]
	v_mfma_f32_16x16x32_bf16 v[28:31], v[122:125], v[110:113], v[28:31]
	v_mfma_f32_16x16x32_bf16 v[24:27], v[126:129], v[110:113], v[24:27]
	v_mfma_f32_16x16x32_bf16 v[20:23], v[130:133], v[110:113], v[20:23]
	v_mfma_f32_16x16x32_bf16 v[16:19], v[118:121], v[114:117], v[16:19]
	v_mfma_f32_16x16x32_bf16 v[12:15], v[122:125], v[114:117], v[12:15]
	v_mfma_f32_16x16x32_bf16 v[8:11], v[126:129], v[114:117], v[8:11]
	v_mfma_f32_16x16x32_bf16 v[4:7], v[130:133], v[114:117], v[4:7]
	v_mfma_f32_16x16x32_bf16 v[64:67], v[118:121], v[80:83], v[64:67]
	v_mfma_f32_16x16x32_bf16 v[60:63], v[122:125], v[80:83], v[60:63]
	v_mfma_f32_16x16x32_bf16 v[68:71], v[130:133], v[80:83], v[52:55]
	s_setprio 0
	v_mov_b32_e32 v0, v198
	s_waitcnt vmcnt(0) lgkmcnt(0)
	s_barrier
; __device__ __forceinline__ unsigned pk2(float lo, float hi) { unsigned r; asm("v_cvt_pk_bf16_f32 %0, %1, %2" : "=v"(r) : "v"(lo), "v"(hi)); return r; }
; __device__ __forceinline__ float bflo(unsigned u) { return __uint_as_float(u << 16); }
; __device__ __forceinline__ float bfhi(unsigned u) { return __uint_as_float(u & 0xffff0000u); }
; __device__ __forceinline__ void gemm_RES(const bf16_t* A, int K, const bf16_t* Bt, const float* xin, float* xout, bf16_t* xb, float* rss, int item, char* lds) {
;     ...
; #pragma unroll
;   for (int m = 0; m < 4; m++) {
;     const int rowg = m0 + wr * 64 + m * 16 + fr;
;     const size_t ro = (size_t)rowg * DM;
;     float sq = 0.f;
; #pragma unroll
;     for (int n = 0; n < 4; n++) {
;       const int col = n0 + wc * 64 + n * 16 + fq * 4;
;       f32x4 xv = *(const f32x4*)(xin + ro + col);
;       const f32x4 xn = xv + acc[m][n];
;       *(f32x4*)(xout + ro + col) = xn;
;       u32x2 w; w[0] = pk2(xn[0], xn[1]); w[1] = pk2(xn[2], xn[3]); *(u32x2*)(xb + ro + col) = w;
;       const float b0 = bflo(w[0]), b1 = bfhi(w[0]), b2 = bflo(w[1]), b3 = bfhi(w[1]);
;       sq += b0 * b0 + b1 * b1 + b2 * b2 + b3 * b3;
;     }
;     sq += __shfl_xor(sq, 16); sq += __shfl_xor(sq, 32);
;     if (fq == 0) unsafeAtomicAdd(rss + rowg, sq);
;   }
	v_readlane_b32 s4, v252, 35
	v_ashrrev_i32_e32 v2, 1, v0
	v_and_b32_e32 v2, 0xffffffc0, v2
	v_bfe_u32 v80, v0, 4, 2
	v_add_u32_e32 v2, s3, v2
	v_and_b32_e32 v1, 64, v0
	v_and_or_b32 v0, v0, 15, v2
	v_lshlrev_b32_e32 v2, 2, v80
	v_or3_b32 v54, v2, v1, s2
	v_ashrrev_i32_e32 v1, 31, v0
	v_lshlrev_b64 v[52:53], 12, v[0:1]
	v_readlane_b32 s18, v252, 49
	v_readlane_b32 s19, v252, 50
	v_lshlrev_b32_e32 v2, 2, v54
	v_readlane_b32 s5, v252, 36
	v_lshl_add_u64 v[52:53], s[18:19], 0, v[52:53]
	v_lshl_add_u64 v[76:77], v[52:53], 0, v[2:3]
	global_load_dwordx4 v[72:75], v[76:77], off
	v_lshlrev_b32_e32 v52, 1, v54
	v_lshlrev_b64 v[54:55], 11, v[0:1]
	v_mov_b32_e32 v53, v3
	v_lshl_add_u64 v[54:55], s[26:27], 0, v[54:55]
	v_lshl_add_u64 v[78:79], v[54:55], 0, v[52:53]
	v_readlane_b32 s6, v252, 37
	v_readlane_b32 s7, v252, 38
	v_readlane_b32 s8, v252, 39
	v_readlane_b32 s9, v252, 40
	v_readlane_b32 s10, v252, 41
	v_readlane_b32 s11, v252, 42
	v_readlane_b32 s12, v252, 43
	v_readlane_b32 s13, v252, 44
	v_readlane_b32 s14, v252, 45
	v_readlane_b32 s15, v252, 46
	v_readlane_b32 s16, v252, 47
	v_readlane_b32 s17, v252, 48
	s_waitcnt vmcnt(0)
	v_pk_add_f32 v[66:67], v[66:67], v[74:75]
	v_pk_add_f32 v[64:65], v[64:65], v[72:73]
	global_store_dwordx4 v[76:77], v[64:67], off
	v_cvt_pk_bf16_f32 v54, v64, v65
	v_cvt_pk_bf16_f32 v55, v66, v67
	global_store_dwordx2 v[78:79], v[54:55], off
	global_load_dwordx4 v[64:67], v[76:77], off offset:64
	s_waitcnt vmcnt(0)
	v_pk_add_f32 v[62:63], v[62:63], v[66:67]
	v_pk_add_f32 v[60:61], v[60:61], v[64:65]
	global_store_dwordx4 v[76:77], v[60:63], off offset:64
	v_cvt_pk_bf16_f32 v64, v60, v61
	v_cvt_pk_bf16_f32 v65, v62, v63
	global_store_dwordx2 v[78:79], v[64:65], off offset:32
	global_load_dwordx4 v[60:63], v[76:77], off offset:128
	v_lshlrev_b32_e32 v66, 16, v54
	v_and_b32_e32 v54, 0xffff0000, v54
	v_mul_f32_e32 v54, v54, v54
	v_lshlrev_b32_e32 v67, 16, v55
	v_fmac_f32_e32 v54, v66, v66
	v_and_b32_e32 v55, 0xffff0000, v55
	v_fmac_f32_e32 v54, v67, v67
	v_fmac_f32_e32 v54, v55, v55
	v_lshlrev_b32_e32 v55, 16, v64
	v_and_b32_e32 v64, 0xffff0000, v64
	v_mul_f32_e32 v64, v64, v64
	v_lshlrev_b32_e32 v66, 16, v65
	v_fmac_f32_e32 v64, v55, v55
	v_and_b32_e32 v65, 0xffff0000, v65
	v_fmac_f32_e32 v64, v66, v66
	v_fmac_f32_e32 v64, v65, v65
	v_add_f32_e32 v54, v54, v64
	s_waitcnt vmcnt(0)
	v_pk_add_f32 v[58:59], v[58:59], v[62:63]
	v_pk_add_f32 v[56:57], v[56:57], v[60:61]
	global_store_dwordx4 v[76:77], v[56:59], off offset:128
	v_cvt_pk_bf16_f32 v62, v56, v57
	v_cvt_pk_bf16_f32 v63, v58, v59
	global_store_dwordx2 v[78:79], v[62:63], off offset:64
	global_load_dwordx4 v[58:61], v[76:77], off offset:192
	v_lshlrev_b32_e32 v55, 16, v62
	v_and_b32_e32 v62, 0xffff0000, v62
	v_mul_f32_e32 v62, v62, v62
	v_lshlrev_b32_e32 v64, 16, v63
	v_fmac_f32_e32 v62, v55, v55
	v_and_b32_e32 v63, 0xffff0000, v63
	v_fmac_f32_e32 v62, v64, v64
	v_fmac_f32_e32 v62, v63, v63
	v_add_f32_e32 v54, v54, v62
	v_and_b32_e32 v57, 64, v218
	v_xor_b32_e32 v56, 16, v218
	v_add_u32_e32 v57, 64, v57
	v_cmp_lt_i32_e32 vcc, v56, v57
	s_waitcnt vmcnt(0)
	v_pk_add_f32 v[58:59], v[68:69], v[58:59]
	s_nop 0
	v_cvt_pk_bf16_f32 v62, v58, v59
	v_pk_add_f32 v[60:61], v[70:71], v[60:61]
	v_and_b32_e32 v64, 0xffff0000, v62
	v_lshlrev_b32_e32 v55, 16, v62
	v_mul_f32_e32 v64, v64, v64
	v_cvt_pk_bf16_f32 v63, v60, v61
	v_fmac_f32_e32 v64, v55, v55
	v_lshlrev_b32_e32 v65, 16, v63
	v_and_b32_e32 v66, 0xffff0000, v63
	v_fmac_f32_e32 v64, v65, v65
	v_cndmask_b32_e32 v56, v218, v56, vcc
	v_fmac_f32_e32 v64, v66, v66
	v_lshlrev_b32_e32 v56, 2, v56
	v_add_f32_e32 v54, v54, v64
	ds_bpermute_b32 v55, v56, v54
	v_xor_b32_e32 v64, 32, v218
	v_cmp_lt_i32_e32 vcc, v64, v57
	global_store_dwordx4 v[76:77], v[58:61], off offset:192
	global_store_dwordx2 v[78:79], v[62:63], off offset:96
	v_cndmask_b32_e32 v57, v218, v64, vcc
	s_waitcnt lgkmcnt(0)
	v_add_f32_e32 v54, v54, v55
	v_lshlrev_b32_e32 v57, 2, v57
	ds_bpermute_b32 v55, v57, v54
	v_cmp_eq_u32_e32 vcc, 0, v80
	s_and_saveexec_b64 s[28:29], vcc
	s_cbranch_execz .LBB0_98
	v_lshl_add_u64 v[58:59], v[0:1], 2, s[24:25]
	s_waitcnt lgkmcnt(0)
	v_add_f32_e32 v1, v54, v55
	global_atomic_add_f32 v[58:59], v1, off

; __device__ __forceinline__ void gemm_mainloop_d(const bf16_t* __restrict__ Ap, int lda, const bf16_t* __restrict__ Bt, int K,
;                                                 int m0, int n0, f32x4 (&acc)[4][4], char* lds) {
;     ...
;   auto dma = [&](int kt, int st) {
;     char* la = lds + st * 32768; char* lb = la + 16384;
; #pragma unroll
;     for (int i = 0; i < 4; i++) {
;       const int row = i * 32 + lrow; const int c = cph ^ ((row >> 1) & 7);
;       __builtin_amdgcn_global_load_lds((const unsigned*)(Ap + (size_t)(m0 + row) * lda + kt * 64 + c * 8), (__attribute__((address_space(3))) unsigned*)(la + i * 4096 + tid * 16), 16, 0, 0);
;       __builtin_amdgcn_global_load_lds((const unsigned*)(Bt + (size_t)(n0 + row) * K + kt * 64 + c * 8), (__attribute__((address_space(3))) unsigned*)(lb + i * 4096 + tid * 16), 16, 0, 0);
;     }
;   };
;   dma(0, 0);
;   asm volatile("s_waitcnt vmcnt(0)" ::: "memory"); __builtin_amdgcn_s_barrier(); asm volatile("" ::: "memory");
;   for (int kt = 0; kt < nk; kt++) {
;     const int st = kt & 1;
;     if (kt + 1 < nk) dma(kt + 1, st ^ 1);
;     const char* la = lds + st * 32768; const char* lb = la + 16384;
;     bf16x8 af[2][4], bfv[2][4];
; #pragma unroll
;     for (int kc = 0; kc < 2; kc++) {
; #pragma unroll
;       for (int m = 0; m < 4; m++) { const int row = wr * 64 + m * 16 + fr; af[kc][m] = *(const bf16x8*)(la + (row * 8 + ((kc * 4 + fq) ^ ((row >> 1) & 7))) * 16); }
; #pragma unroll
;       for (int n = 0; n < 4; n++) { const int row = wc * 64 + n * 16 + fr; bfv[kc][n] = *(const bf16x8*)(lb + (row * 8 + ((kc * 4 + fq) ^ ((row >> 1) & 7))) * 16); }
;     }
;     __builtin_amdgcn_s_setprio(1);
; #pragma unroll
;     for (int kc = 0; kc < 2; kc++)
; #pragma unroll
;       for (int m = 0; m < 4; m++)
; #pragma unroll
;         for (int n = 0; n < 4; n++) acc[m][n] = __builtin_amdgcn_mfma_f32_16x16x32_bf16(bfv[kc][n], af[kc][m], acc[m][n], 0, 0, 0);
;     __builtin_amdgcn_s_setprio(0);
;     asm volatile("s_waitcnt vmcnt(0) lgkmcnt(0)" ::: "memory"); __builtin_amdgcn_s_barrier(); asm volatile("" ::: "memory");
;   }
.LBB0_109:
	s_setprio 3
	s_and_b32 s34, s25, 0x8000
	s_xor_b32 s35, s34, 0x8000
	s_add_i32 s35, s35, vcc_hi
	s_mov_b32 m0, s35
	s_add_i32 vcc_lo, s35, 0x4000
	global_load_lds_dwordx4 v150, s[46:47]
	s_mov_b32 m0, vcc_lo
	s_add_i32 vcc_lo, s35, 0x1000
	global_load_lds_dwordx4 v151, s[46:47]
	s_mov_b32 m0, vcc_lo
	s_add_i32 vcc_lo, s35, 0x5000
	global_load_lds_dwordx4 v152, s[46:47]
	s_mov_b32 m0, vcc_lo
	s_add_i32 vcc_lo, s35, 0x2000
	global_load_lds_dwordx4 v153, s[46:47]
	s_mov_b32 m0, vcc_lo
	s_add_i32 vcc_lo, s35, 0x6000
	global_load_lds_dwordx4 v154, s[46:47]
	s_mov_b32 m0, vcc_lo
	s_add_i32 vcc_lo, s35, 0x3000
	global_load_lds_dwordx4 v155, s[46:47]
	s_mov_b32 m0, vcc_lo
	s_add_i32 vcc_lo, s35, 0x7000
	global_load_lds_dwordx4 v156, s[46:47]
	s_mov_b32 m0, vcc_lo
	s_nop 0
	global_load_lds_dwordx4 v157, s[46:47]
	s_setprio 0
	v_add_u32_e32 v150, 0x80, v150
	v_add_u32_e32 v151, 0x80, v151
	v_add_u32_e32 v152, 0x80, v152
	v_add_u32_e32 v153, 0x80, v153
	v_add_u32_e32 v154, 0x80, v154
	v_add_u32_e32 v155, 0x80, v155
	v_add_u32_e32 v156, 0x80, v156
	v_add_u32_e32 v157, 0x80, v157
	v_add_u32_e32 v98, s34, v85
	v_add_u32_e32 v114, s34, v84
	v_add_u32_e32 v130, s34, v83
	v_add_u32_e32 v146, s34, v2
	ds_read_b128 v[86:89], v98
	ds_read_b128 v[90:93], v98 offset:2048
	ds_read_b128 v[94:97], v98 offset:4096
	ds_read_b128 v[98:101], v98 offset:6144
	ds_read_b128 v[102:105], v114 offset:16384
	ds_read_b128 v[106:109], v114 offset:18432
	ds_read_b128 v[110:113], v114 offset:20480
	ds_read_b128 v[114:117], v114 offset:22528
	ds_read_b128 v[118:121], v130
	ds_read_b128 v[122:125], v130 offset:2048
	ds_read_b128 v[126:129], v130 offset:4096
	ds_read_b128 v[130:133], v130 offset:6144
	ds_read_b128 v[134:137], v146 offset:16384
	ds_read_b128 v[138:141], v146 offset:18432
	ds_read_b128 v[142:145], v146 offset:20480
	ds_read_b128 v[146:149], v146 offset:22528
	s_setprio 1
	s_waitcnt lgkmcnt(0)
	v_mfma_f32_16x16x32_bf16 v[64:67], v[102:105], v[86:89], v[64:67]
	v_mfma_f32_16x16x32_bf16 v[60:63], v[106:109], v[86:89], v[60:63]
	v_mfma_f32_16x16x32_bf16 v[56:59], v[110:113], v[86:89], v[56:59]
	v_mfma_f32_16x16x32_bf16 v[52:55], v[114:117], v[86:89], v[52:55]
	v_mfma_f32_16x16x32_bf16 v[48:51], v[102:105], v[90:93], v[48:51]
	v_mfma_f32_16x16x32_bf16 v[44:47], v[106:109], v[90:93], v[44:47]
	v_mfma_f32_16x16x32_bf16 v[40:43], v[110:113], v[90:93], v[40:43]
	v_mfma_f32_16x16x32_bf16 v[36:39], v[114:117], v[90:93], v[36:39]
	v_mfma_f32_16x16x32_bf16 v[32:35], v[102:105], v[94:97], v[32:35]
	v_mfma_f32_16x16x32_bf16 v[28:31], v[106:109], v[94:97], v[28:31]
	v_mfma_f32_16x16x32_bf16 v[24:27], v[110:113], v[94:97], v[24:27]
	v_mfma_f32_16x16x32_bf16 v[20:23], v[114:117], v[94:97], v[20:23]
	v_mfma_f32_16x16x32_bf16 v[16:19], v[102:105], v[98:101], v[16:19]
	v_mfma_f32_16x16x32_bf16 v[12:15], v[106:109], v[98:101], v[12:15]
	v_mfma_f32_16x16x32_bf16 v[8:11], v[110:113], v[98:101], v[8:11]
	v_mfma_f32_16x16x32_bf16 v[4:7], v[114:117], v[98:101], v[4:7]
	v_mfma_f32_16x16x32_bf16 v[64:67], v[134:137], v[118:121], v[64:67]
	v_mfma_f32_16x16x32_bf16 v[60:63], v[138:141], v[118:121], v[60:63]
	v_mfma_f32_16x16x32_bf16 v[56:59], v[142:145], v[118:121], v[56:59]
	v_mfma_f32_16x16x32_bf16 v[52:55], v[146:149], v[118:121], v[52:55]
	v_mfma_f32_16x16x32_bf16 v[48:51], v[134:137], v[122:125], v[48:51]
	v_mfma_f32_16x16x32_bf16 v[44:47], v[138:141], v[122:125], v[44:47]
	v_mfma_f32_16x16x32_bf16 v[40:43], v[142:145], v[122:125], v[40:43]
	v_mfma_f32_16x16x32_bf16 v[36:39], v[146:149], v[122:125], v[36:39]
	v_mfma_f32_16x16x32_bf16 v[32:35], v[134:137], v[126:129], v[32:35]
	v_mfma_f32_16x16x32_bf16 v[28:31], v[138:141], v[126:129], v[28:31]
	v_mfma_f32_16x16x32_bf16 v[24:27], v[142:145], v[126:129], v[24:27]
	v_mfma_f32_16x16x32_bf16 v[20:23], v[146:149], v[126:129], v[20:23]
	v_mfma_f32_16x16x32_bf16 v[16:19], v[134:137], v[130:133], v[16:19]
	v_mfma_f32_16x16x32_bf16 v[12:15], v[138:141], v[130:133], v[12:15]
	v_mfma_f32_16x16x32_bf16 v[8:11], v[142:145], v[130:133], v[8:11]
	v_mfma_f32_16x16x32_bf16 v[4:7], v[146:149], v[130:133], v[4:7]
	s_setprio 0
	s_waitcnt vmcnt(0) lgkmcnt(0)
	s_barrier
	s_add_u32 s26, s26, 0x80
	s_addc_u32 s27, s27, 0
	s_add_i32 s25, s25, 0x8000
	s_cmpk_lg_i32 s26, 0x780
	s_cbranch_scc1 .LBB0_109
; __device__ __forceinline__ unsigned char* WS(const Params& p) { unsigned z = 0; asm volatile("" : "+s"(z)); return p.ws + z; }
; __device__ __forceinline__ void gemm_mainloop_d(const bf16_t* __restrict__ Ap, int lda, const bf16_t* __restrict__ Bt, int K,
;                                                 int m0, int n0, f32x4 (&acc)[4][4], char* lds) {
;     ...
;     const char* la = lds + st * 32768; const char* lb = la + 16384;
;     bf16x8 af[2][4], bfv[2][4];
; #pragma unroll
;     for (int kc = 0; kc < 2; kc++) {
; #pragma unroll
;       for (int m = 0; m < 4; m++) { const int row = wr * 64 + m * 16 + fr; af[kc][m] = *(const bf16x8*)(la + (row * 8 + ((kc * 4 + fq) ^ ((row >> 1) & 7))) * 16); }
; #pragma unroll
;       for (int n = 0; n < 4; n++) { const int row = wc * 64 + n * 16 + fr; bfv[kc][n] = *(const bf16x8*)(lb + (row * 8 + ((kc * 4 + fq) ^ ((row >> 1) & 7))) * 16); }
;     }
;     __builtin_amdgcn_s_setprio(1);
; #pragma unroll
;     for (int kc = 0; kc < 2; kc++)
; #pragma unroll
;       for (int m = 0; m < 4; m++)
; #pragma unroll
;         for (int n = 0; n < 4; n++) acc[m][n] = __builtin_amdgcn_mfma_f32_16x16x32_bf16(bfv[kc][n], af[kc][m], acc[m][n], 0, 0, 0);
;     __builtin_amdgcn_s_setprio(0);
;     asm volatile("s_waitcnt vmcnt(0) lgkmcnt(0)" ::: "memory"); __builtin_amdgcn_s_barrier(); asm volatile("" ::: "memory");
;   }
; __device__ __forceinline__ void gemm_GU(const Params& p, int item, char* lds) {
;     ...
;   const float* rssg = (const float*)(WS(p) + OFF_RSS) + T + m0;
;   bf16_t* U = (bf16_t*)(WS(p) + OFF_U);
; #pragma unroll
;   for (int m = 0; m < 4; m++) {
;     const int rl = wr * 64 + m * 16 + fr; const float r = rsqrtf(rssg[rl] * (1.f / 1024.f) + 1e-6f);
	v_add_u32_e32 v0, 0, v85
	ds_read_b128 v[68:71], v0 offset:32768
	ds_read_b128 v[72:75], v0 offset:34816
	ds_read_b128 v[76:79], v0 offset:36864
	ds_read_b128 v[86:89], v0 offset:38912
	v_add_u32_e32 v0, 0, v84
	ds_read_b128 v[90:93], v0 offset:49152
	ds_read_b128 v[94:97], v0 offset:51200
	ds_read_b128 v[98:101], v0 offset:53248
	ds_read_b128 v[102:105], v0 offset:55296
	v_add_u32_e32 v0, 0, v83
	ds_read_b128 v[80:83], v0 offset:32768
	ds_read_b128 v[106:109], v0 offset:34816
	ds_read_b128 v[110:113], v0 offset:36864
	ds_read_b128 v[114:117], v0 offset:38912
	v_add_u32_e32 v0, 0, v2
	ds_read_b128 v[118:121], v0 offset:49152
	ds_read_b128 v[122:125], v0 offset:51200
	ds_read_b128 v[126:129], v0 offset:53248
	ds_read_b128 v[130:133], v0 offset:55296
	s_setprio 1
	s_waitcnt lgkmcnt(0)
	v_mfma_f32_16x16x32_bf16 v[64:67], v[90:93], v[68:71], v[64:67]
	v_mfma_f32_16x16x32_bf16 v[60:63], v[94:97], v[68:71], v[60:63]
	v_mfma_f32_16x16x32_bf16 v[56:59], v[98:101], v[68:71], v[56:59]
	v_mfma_f32_16x16x32_bf16 v[52:55], v[102:105], v[68:71], v[52:55]
	v_mfma_f32_16x16x32_bf16 v[48:51], v[90:93], v[72:75], v[48:51]
	v_mfma_f32_16x16x32_bf16 v[44:47], v[94:97], v[72:75], v[44:47]
	v_mfma_f32_16x16x32_bf16 v[68:71], v[98:101], v[72:75], v[40:43]
	v_mfma_f32_16x16x32_bf16 v[72:75], v[102:105], v[72:75], v[36:39]
	v_mfma_f32_16x16x32_bf16 v[32:35], v[90:93], v[76:79], v[32:35]
	v_mfma_f32_16x16x32_bf16 v[28:31], v[94:97], v[76:79], v[28:31]
	v_mfma_f32_16x16x32_bf16 v[134:137], v[98:101], v[76:79], v[24:27]
	v_mfma_f32_16x16x32_bf16 v[76:79], v[102:105], v[76:79], v[20:23]
	v_mfma_f32_16x16x32_bf16 v[16:19], v[90:93], v[86:89], v[16:19]
	v_mfma_f32_16x16x32_bf16 v[12:15], v[94:97], v[86:89], v[12:15]
	v_mfma_f32_16x16x32_bf16 v[90:93], v[98:101], v[86:89], v[8:11]
	v_mfma_f32_16x16x32_bf16 v[84:87], v[102:105], v[86:89], v[4:7]
	v_mfma_f32_16x16x32_bf16 v[64:67], v[118:121], v[80:83], v[64:67]
	v_mfma_f32_16x16x32_bf16 v[60:63], v[122:125], v[80:83], v[60:63]
	v_mfma_f32_16x16x32_bf16 v[56:59], v[126:129], v[80:83], v[56:59]
	v_mfma_f32_16x16x32_bf16 v[52:55], v[130:133], v[80:83], v[52:55]
	v_mfma_f32_16x16x32_bf16 v[40:43], v[118:121], v[106:109], v[48:51]
	v_mfma_f32_16x16x32_bf16 v[48:51], v[122:125], v[106:109], v[44:47]
	v_mfma_f32_16x16x32_bf16 v[36:39], v[126:129], v[106:109], v[68:71]
	v_mfma_f32_16x16x32_bf16 v[44:47], v[130:133], v[106:109], v[72:75]
	v_mfma_f32_16x16x32_bf16 v[24:27], v[118:121], v[110:113], v[32:35]
	v_mfma_f32_16x16x32_bf16 v[32:35], v[122:125], v[110:113], v[28:31]
	v_mfma_f32_16x16x32_bf16 v[20:23], v[126:129], v[110:113], v[134:137]
	v_mfma_f32_16x16x32_bf16 v[28:31], v[130:133], v[110:113], v[76:79]
	v_mfma_f32_16x16x32_bf16 v[8:11], v[118:121], v[114:117], v[16:19]
	v_mfma_f32_16x16x32_bf16 v[16:19], v[122:125], v[114:117], v[12:15]
	v_mfma_f32_16x16x32_bf16 v[4:7], v[126:129], v[114:117], v[90:93]
	v_mfma_f32_16x16x32_bf16 v[12:15], v[130:133], v[114:117], v[84:87]
	s_setprio 0
	v_mov_b32_e32 v2, v198
	s_mov_b32 s25, s89
	s_waitcnt vmcnt(0) lgkmcnt(0)
	s_barrier
	s_add_u32 s34, s46, s25
	s_addc_u32 s35, s47, 0
	s_ashr_i32 s25, s24, 31
	v_and_b32_e32 v0, 15, v2
	s_lshl_b64 s[26:27], s[24:25], 2
	v_ashrrev_i32_e32 v1, 1, v2
	s_movk_i32 s4, 0xffc0
	s_add_u32 s26, s34, s26
	v_and_or_b32 v0, v1, s4, v0
	s_addc_u32 s27, s35, s27
	v_ashrrev_i32_e32 v1, 31, v0
	v_lshl_add_u64 v[68:69], v[0:1], 2, s[26:27]
	s_mov_b32 s26, 0xff9c000
	v_add_co_u32_e32 v70, vcc, s26, v68
	s_mov_b32 s25, s89
	s_nop 0
	v_addc_co_u32_e32 v71, vcc, 0, v69, vcc
	global_load_dword v74, v[70:71], off
	v_mov_b32_e32 v71, v64
	v_mov_b32_e32 v64, v61
	v_mov_b32_e32 v61, v66
	v_mov_b32_e32 v66, v63
	v_mov_b32_e32 v63, v56
	v_mov_b32_e32 v56, v53
	v_mov_b32_e32 v70, v60
	v_mov_b32_e32 v60, v62
	v_mov_b32_e32 v62, v52
	v_mov_b32_e32 v72, v54
	v_mov_b32_e32 v73, v58
	v_mov_b32_e32 v58, v55
	v_lshrrev_b32_e32 v1, 1, v2
	v_lshrrev_b32_e32 v2, 2, v2
	s_add_u32 s26, s46, s25
	v_and_b32_e32 v52, 12, v2
	v_add_u32_e32 v2, s24, v0
	s_addc_u32 s27, s47, 0
	s_mov_b64 s[24:25], 0xff9c000
	v_lshl_add_u64 v[54:55], v[68:69], 0, s[24:25]
	s_add_u32 s24, s26, 0x768000
	v_and_b32_e32 v1, 32, v1
	s_addc_u32 s25, s27, 0
	s_ashr_i32 s26, s31, 1
	v_or3_b32 v52, v1, s26, v52
	v_mov_b64_e32 v[0:1], s[24:25]
	v_mad_i64_i32 v[68:69], s[24:25], v2, s33, v[0:1]
	s_add_i32 s30, s30, s77
	s_add_i32 s29, s29, s2
	s_add_i32 s28, s28, s3
	s_cmpk_gt_i32 s30, 0x15ff
	s_waitcnt vmcnt(0)
; __device__ __forceinline__ unsigned pk2(float lo, float hi) { unsigned r; asm("v_cvt_pk_bf16_f32 %0, %1, %2" : "=v"(r) : "v"(lo), "v"(hi)); return r; }
; __device__ __forceinline__ float sigmoidf_(float x) { return __builtin_amdgcn_rcpf(1.0f + __expf(-x)); }
; __device__ __forceinline__ void gemm_GU(const Params& p, int item, char* lds) {
;     ...
;   for (int m = 0; m < 4; m++) {
;     const int rl = wr * 64 + m * 16 + fr; const float r = rsqrtf(rssg[rl] * (1.f / 1024.f) + 1e-6f);
; #pragma unroll
;     for (int i = 0; i < 2; i++) {
;       f32x4 g = acc[m][2 * i] * r, u = acc[m][2 * i + 1] * r, o;
; #pragma unroll
;       for (int j = 0; j < 4; j++) o[j] = g[j] * sigmoidf_(g[j]) * u[j];
;       const int col = (n0 >> 1) + wc * 32 + i * 16 + fq * 4;
;       u32x2 w; w[0] = pk2(o[0], o[1]); w[1] = pk2(o[2], o[3]);
;       *(u32x2*)(U + (size_t)(m0 + rl) * DFF + col) = w;
;     }
;   }
	v_fmamk_f32 v53, v74, 0x3a800000, v200
	v_mul_f32_e32 v74, 0x4b800000, v53
	v_cmp_gt_f32_e32 vcc, s83, v53
	s_nop 1
	v_cndmask_b32_e32 v53, v53, v74, vcc
	v_rsq_f32_e32 v74, v53
	v_ashrrev_i32_e32 v53, 31, v52
	v_lshlrev_b64 v[52:53], 1, v[52:53]
	v_lshl_add_u64 v[68:69], v[68:69], 0, v[52:53]
	v_mul_f32_e32 v75, 0x45800000, v74
	v_cndmask_b32_e32 v74, v74, v75, vcc
	v_pk_mul_f32 v[60:61], v[60:61], v[74:75] op_sel_hi:[1,0]
	v_pk_mul_f32 v[70:71], v[70:71], v[74:75] op_sel_hi:[1,0]
	v_pk_mul_f32 v[64:65], v[64:65], v[74:75] op_sel_hi:[1,0]
	v_pk_mul_f32 v[66:67], v[66:67], v[74:75] op_sel_hi:[1,0]
	v_mul_f32_e32 v76, 0xbfb8aa3b, v61
	v_pk_mul_f32 v[62:63], v[62:63], v[74:75] op_sel_hi:[1,0]
	v_pk_mul_f32 v[56:57], v[56:57], v[74:75] op_sel_hi:[1,0]
	v_pk_mul_f32 v[72:73], v[72:73], v[74:75] op_sel_hi:[1,0]
	v_pk_mul_f32 v[58:59], v[58:59], v[74:75] op_sel_hi:[1,0]
	v_mul_f32_e32 v74, 0xbfb8aa3b, v71
	v_mul_f32_e32 v75, 0xbfb8aa3b, v65
	v_mul_f32_e32 v77, 0xbfb8aa3b, v67
	v_exp_f32_e32 v76, v76
	v_exp_f32_e32 v74, v74
	v_exp_f32_e32 v75, v75
	v_exp_f32_e32 v77, v77
	v_add_f32_e32 v76, 1.0, v76
	v_mul_f32_e32 v79, 0xbfb8aa3b, v57
	v_add_f32_e32 v74, 1.0, v74
	v_add_f32_e32 v75, 1.0, v75
	v_add_f32_e32 v77, 1.0, v77
	v_rcp_f32_e32 v76, v76
	v_mul_f32_e32 v80, 0xbfb8aa3b, v73
	v_exp_f32_e32 v79, v79
	v_rcp_f32_e32 v74, v74
	v_rcp_f32_e32 v75, v75
	v_rcp_f32_e32 v77, v77
	v_mul_f32_e32 v78, 0xbfb8aa3b, v63
	v_mul_f32_e32 v81, 0xbfb8aa3b, v59
	v_exp_f32_e32 v80, v80
	v_exp_f32_e32 v78, v78
	v_exp_f32_e32 v81, v81
	v_mul_f32_e32 v61, v61, v76
	v_add_f32_e32 v79, 1.0, v79
	v_mul_f32_e32 v71, v71, v74
	v_mul_f32_e32 v65, v65, v75
	v_mul_f32_e32 v67, v67, v77
	v_mul_f32_e32 v61, v60, v61
	v_add_f32_e32 v80, 1.0, v80
	v_rcp_f32_e32 v79, v79
	v_mul_f32_e32 v70, v70, v71
	v_mul_f32_e32 v64, v64, v65
	v_mul_f32_e32 v65, v66, v67
	v_cvt_pk_bf16_f32 v60, v70, v64
	v_cvt_pk_bf16_f32 v61, v61, v65
	v_add_f32_e32 v78, 1.0, v78
	global_store_dwordx2 v[68:69], v[60:61], off
	v_rcp_f32_e32 v60, v80
	v_add_f32_e32 v61, 1.0, v81
	v_rcp_f32_e32 v78, v78
	v_rcp_f32_e32 v61, v61
	v_mul_f32_e32 v57, v57, v79
	v_mul_f32_e32 v56, v56, v57
	v_mul_f32_e32 v57, v73, v60
	v_mul_f32_e32 v63, v63, v78
	v_mul_f32_e32 v57, v72, v57
	v_mul_f32_e32 v59, v59, v61
	v_mul_f32_e32 v62, v62, v63
	v_mul_f32_e32 v58, v58, v59
	v_cvt_pk_bf16_f32 v56, v62, v56
	v_cvt_pk_bf16_f32 v57, v57, v58
	global_store_dwordx2 v[68:69], v[56:57], off offset:32
	global_load_dword v58, v[54:55], off offset:64
	v_mov_b32_e32 v57, v40
	v_mov_b32_e32 v40, v49
	v_mov_b32_e32 v49, v42
	v_mov_b32_e32 v42, v51
	v_mov_b32_e32 v51, v36
	v_mov_b32_e32 v36, v45
	v_mov_b32_e32 v45, v38
	v_mov_b32_e32 v38, v47
	v_mov_b32_e32 v56, v48
	v_mov_b32_e32 v48, v50
	v_mov_b32_e32 v50, v44
	v_mov_b32_e32 v44, v46
	v_add_u32_e32 v46, 16, v2
	s_waitcnt vmcnt(0)
	v_fmamk_f32 v47, v58, 0x3a800000, v200
	v_mul_f32_e32 v58, 0x4b800000, v47
	v_cmp_gt_f32_e32 vcc, s83, v47
	s_nop 1
	v_cndmask_b32_e32 v47, v47, v58, vcc
	v_rsq_f32_e32 v58, v47
	v_mad_i64_i32 v[46:47], s[24:25], v46, s33, v[0:1]
	v_lshl_add_u64 v[46:47], v[46:47], 0, v[52:53]
	v_mul_f32_e32 v59, 0x45800000, v58
	v_cndmask_b32_e32 v58, v58, v59, vcc
	v_pk_mul_f32 v[56:57], v[56:57], v[58:59] op_sel_hi:[1,0]
	v_pk_mul_f32 v[40:41], v[40:41], v[58:59] op_sel_hi:[1,0]
	v_pk_mul_f32 v[48:49], v[48:49], v[58:59] op_sel_hi:[1,0]
	v_pk_mul_f32 v[42:43], v[42:43], v[58:59] op_sel_hi:[1,0]
	v_pk_mul_f32 v[36:37], v[36:37], v[58:59] op_sel_hi:[1,0]
	v_pk_mul_f32 v[38:39], v[38:39], v[58:59] op_sel_hi:[1,0]
	v_pk_mul_f32 v[50:51], v[50:51], v[58:59] op_sel_hi:[1,0]
	v_pk_mul_f32 v[44:45], v[44:45], v[58:59] op_sel_hi:[1,0]
	v_mul_f32_e32 v58, 0xbfb8aa3b, v57
	v_mul_f32_e32 v59, 0xbfb8aa3b, v41
	v_mul_f32_e32 v60, 0xbfb8aa3b, v49
	v_mul_f32_e32 v61, 0xbfb8aa3b, v43
	v_mul_f32_e32 v63, 0xbfb8aa3b, v37
	v_mul_f32_e32 v65, 0xbfb8aa3b, v39
	v_mul_f32_e32 v62, 0xbfb8aa3b, v51
	v_mul_f32_e32 v64, 0xbfb8aa3b, v45
	v_exp_f32_e32 v58, v58
	v_exp_f32_e32 v59, v59
	v_exp_f32_e32 v60, v60
	v_exp_f32_e32 v61, v61
	v_exp_f32_e32 v63, v63
	v_exp_f32_e32 v65, v65
	v_exp_f32_e32 v62, v62
	v_exp_f32_e32 v64, v64
	v_add_f32_e32 v58, 1.0, v58
	v_add_f32_e32 v59, 1.0, v59
	v_add_f32_e32 v60, 1.0, v60
	v_add_f32_e32 v61, 1.0, v61
	v_add_f32_e32 v63, 1.0, v63
	v_add_f32_e32 v65, 1.0, v65
	v_add_f32_e32 v62, 1.0, v62
	v_add_f32_e32 v64, 1.0, v64
	v_rcp_f32_e32 v58, v58
	v_rcp_f32_e32 v59, v59
	v_rcp_f32_e32 v60, v60
	v_rcp_f32_e32 v61, v61
	v_rcp_f32_e32 v63, v63
	v_rcp_f32_e32 v65, v65
	v_rcp_f32_e32 v62, v62
	v_rcp_f32_e32 v64, v64
	v_mul_f32_e32 v57, v57, v58
	v_mul_f32_e32 v41, v41, v59
	v_mul_f32_e32 v49, v49, v60
	v_mul_f32_e32 v43, v43, v61
	v_mul_f32_e32 v37, v37, v63
	v_mul_f32_e32 v39, v39, v65
	v_mul_f32_e32 v51, v51, v62
	v_mul_f32_e32 v45, v45, v64
	v_mul_f32_e32 v56, v56, v57
	v_mul_f32_e32 v40, v40, v41
	v_mul_f32_e32 v41, v48, v49
	v_mul_f32_e32 v42, v42, v43
	v_mul_f32_e32 v48, v36, v37
	v_mul_f32_e32 v39, v38, v39
	v_cvt_pk_bf16_f32 v36, v56, v40
	v_cvt_pk_bf16_f32 v37, v41, v42
	v_mul_f32_e32 v43, v50, v51
	v_mul_f32_e32 v44, v44, v45
	v_cvt_pk_bf16_f32 v38, v43, v48
	v_cvt_pk_bf16_f32 v39, v44, v39
	global_store_dwordx2 v[46:47], v[36:37], off
	global_store_dwordx2 v[46:47], v[38:39], off offset:32
	global_load_dword v38, v[54:55], off offset:128
	v_mov_b32_e32 v37, v24
	v_mov_b32_e32 v24, v33
	v_mov_b32_e32 v33, v26
	v_mov_b32_e32 v26, v35
	v_mov_b32_e32 v35, v20
	v_mov_b32_e32 v20, v29
	v_mov_b32_e32 v29, v22
	v_mov_b32_e32 v22, v31
	v_mov_b32_e32 v36, v32
	v_mov_b32_e32 v32, v34
	v_mov_b32_e32 v34, v28
	v_mov_b32_e32 v28, v30
	v_add_u32_e32 v30, 32, v2
	v_add_u32_e32 v2, 48, v2
	s_waitcnt vmcnt(0)
; __device__ __forceinline__ unsigned pk2(float lo, float hi) { unsigned r; asm("v_cvt_pk_bf16_f32 %0, %1, %2" : "=v"(r) : "v"(lo), "v"(hi)); return r; }
; __device__ __forceinline__ float sigmoidf_(float x) { return __builtin_amdgcn_rcpf(1.0f + __expf(-x)); }
; __device__ __forceinline__ void gemm_GU(const Params& p, int item, char* lds) {
;     ...
;   for (int m = 0; m < 4; m++) {
;     const int rl = wr * 64 + m * 16 + fr; const float r = rsqrtf(rssg[rl] * (1.f / 1024.f) + 1e-6f);
; #pragma unroll
;     for (int i = 0; i < 2; i++) {
;       f32x4 g = acc[m][2 * i] * r, u = acc[m][2 * i + 1] * r, o;
; #pragma unroll
;       for (int j = 0; j < 4; j++) o[j] = g[j] * sigmoidf_(g[j]) * u[j];
;       const int col = (n0 >> 1) + wc * 32 + i * 16 + fq * 4;
;       u32x2 w; w[0] = pk2(o[0], o[1]); w[1] = pk2(o[2], o[3]);
;       *(u32x2*)(U + (size_t)(m0 + rl) * DFF + col) = w;
;     }
;   }
;   __syncthreads();
	v_fmamk_f32 v31, v38, 0x3a800000, v200
	v_mul_f32_e32 v38, 0x4b800000, v31
	v_cmp_gt_f32_e32 vcc, s83, v31
	s_nop 1
	v_cndmask_b32_e32 v31, v31, v38, vcc
	v_rsq_f32_e32 v38, v31
	v_mad_i64_i32 v[30:31], s[24:25], v30, s33, v[0:1]
	v_lshl_add_u64 v[30:31], v[30:31], 0, v[52:53]
	v_mul_f32_e32 v39, 0x45800000, v38
	v_cndmask_b32_e32 v38, v38, v39, vcc
	v_pk_mul_f32 v[36:37], v[36:37], v[38:39] op_sel_hi:[1,0]
	v_pk_mul_f32 v[24:25], v[24:25], v[38:39] op_sel_hi:[1,0]
	v_pk_mul_f32 v[32:33], v[32:33], v[38:39] op_sel_hi:[1,0]
	v_pk_mul_f32 v[26:27], v[26:27], v[38:39] op_sel_hi:[1,0]
	v_pk_mul_f32 v[20:21], v[20:21], v[38:39] op_sel_hi:[1,0]
	v_pk_mul_f32 v[22:23], v[22:23], v[38:39] op_sel_hi:[1,0]
	v_pk_mul_f32 v[34:35], v[34:35], v[38:39] op_sel_hi:[1,0]
	v_pk_mul_f32 v[28:29], v[28:29], v[38:39] op_sel_hi:[1,0]
	v_mul_f32_e32 v38, 0xbfb8aa3b, v37
	v_mul_f32_e32 v39, 0xbfb8aa3b, v25
	v_mul_f32_e32 v40, 0xbfb8aa3b, v33
	v_mul_f32_e32 v41, 0xbfb8aa3b, v27
	v_mul_f32_e32 v43, 0xbfb8aa3b, v21
	v_mul_f32_e32 v45, 0xbfb8aa3b, v23
	v_mul_f32_e32 v42, 0xbfb8aa3b, v35
	v_mul_f32_e32 v44, 0xbfb8aa3b, v29
	v_exp_f32_e32 v38, v38
	v_exp_f32_e32 v39, v39
	v_exp_f32_e32 v40, v40
	v_exp_f32_e32 v41, v41
	v_exp_f32_e32 v43, v43
	v_exp_f32_e32 v45, v45
	v_exp_f32_e32 v42, v42
	v_exp_f32_e32 v44, v44
	v_add_f32_e32 v38, 1.0, v38
	v_add_f32_e32 v39, 1.0, v39
	v_add_f32_e32 v40, 1.0, v40
	v_add_f32_e32 v41, 1.0, v41
	v_add_f32_e32 v43, 1.0, v43
	v_add_f32_e32 v45, 1.0, v45
	v_add_f32_e32 v42, 1.0, v42
	v_add_f32_e32 v44, 1.0, v44
	v_rcp_f32_e32 v38, v38
	v_rcp_f32_e32 v39, v39
	v_rcp_f32_e32 v40, v40
	v_rcp_f32_e32 v41, v41
	v_rcp_f32_e32 v43, v43
	v_rcp_f32_e32 v45, v45
	v_rcp_f32_e32 v42, v42
	v_rcp_f32_e32 v44, v44
	v_mul_f32_e32 v37, v37, v38
	v_mul_f32_e32 v25, v25, v39
	v_mul_f32_e32 v33, v33, v40
	v_mul_f32_e32 v27, v27, v41
	v_mul_f32_e32 v21, v21, v43
	v_mul_f32_e32 v23, v23, v45
	v_mul_f32_e32 v35, v35, v42
	v_mul_f32_e32 v29, v29, v44
	v_mul_f32_e32 v36, v36, v37
	v_mul_f32_e32 v24, v24, v25
	v_mul_f32_e32 v25, v32, v33
	v_mul_f32_e32 v26, v26, v27
	v_mul_f32_e32 v32, v20, v21
	v_mul_f32_e32 v23, v22, v23
	v_cvt_pk_bf16_f32 v20, v36, v24
	v_cvt_pk_bf16_f32 v21, v25, v26
	v_mul_f32_e32 v27, v34, v35
	v_mul_f32_e32 v28, v28, v29
	v_cvt_pk_bf16_f32 v22, v27, v32
	v_cvt_pk_bf16_f32 v23, v28, v23
	global_store_dwordx2 v[30:31], v[20:21], off
	global_store_dwordx2 v[30:31], v[22:23], off offset:32
	global_load_dword v22, v[54:55], off offset:192
	v_mov_b32_e32 v20, v16
	v_mov_b32_e32 v16, v18
	v_mov_b32_e32 v18, v12
	v_mov_b32_e32 v12, v14
	v_mov_b32_e32 v21, v8
	v_mov_b32_e32 v8, v17
	v_mov_b32_e32 v17, v10
	v_mov_b32_e32 v10, v19
	v_mov_b32_e32 v19, v4
	v_mov_b32_e32 v4, v13
	v_mov_b32_e32 v13, v6
	v_mov_b32_e32 v6, v15
	v_mad_i64_i32 v[0:1], s[24:25], v2, s33, v[0:1]
	v_lshl_add_u64 v[0:1], v[0:1], 0, v[52:53]
	s_waitcnt vmcnt(0)
	v_fmamk_f32 v14, v22, 0x3a800000, v200
	v_mul_f32_e32 v15, 0x4b800000, v14
	v_cmp_gt_f32_e32 vcc, s83, v14
	s_nop 1
	v_cndmask_b32_e32 v14, v14, v15, vcc
	v_rsq_f32_e32 v14, v14
	s_nop 0
	v_mul_f32_e32 v2, 0x45800000, v14
	v_cndmask_b32_e32 v2, v14, v2, vcc
	v_pk_mul_f32 v[14:15], v[20:21], v[2:3] op_sel_hi:[1,0]
	v_pk_mul_f32 v[8:9], v[8:9], v[2:3] op_sel_hi:[1,0]
	v_pk_mul_f32 v[16:17], v[16:17], v[2:3] op_sel_hi:[1,0]
	v_pk_mul_f32 v[10:11], v[10:11], v[2:3] op_sel_hi:[1,0]
	v_pk_mul_f32 v[4:5], v[4:5], v[2:3] op_sel_hi:[1,0]
	v_pk_mul_f32 v[6:7], v[6:7], v[2:3] op_sel_hi:[1,0]
	v_pk_mul_f32 v[18:19], v[18:19], v[2:3] op_sel_hi:[1,0]
	v_pk_mul_f32 v[12:13], v[12:13], v[2:3] op_sel_hi:[1,0]
	v_mul_f32_e32 v2, 0xbfb8aa3b, v15
	v_mul_f32_e32 v20, 0xbfb8aa3b, v9
	v_mul_f32_e32 v21, 0xbfb8aa3b, v17
	v_mul_f32_e32 v22, 0xbfb8aa3b, v11
	v_mul_f32_e32 v24, 0xbfb8aa3b, v5
	v_mul_f32_e32 v26, 0xbfb8aa3b, v7
	v_mul_f32_e32 v23, 0xbfb8aa3b, v19
	v_mul_f32_e32 v25, 0xbfb8aa3b, v13
	v_exp_f32_e32 v2, v2
	v_exp_f32_e32 v20, v20
	v_exp_f32_e32 v21, v21
	v_exp_f32_e32 v22, v22
	v_exp_f32_e32 v24, v24
	v_exp_f32_e32 v26, v26
	v_exp_f32_e32 v23, v23
	v_exp_f32_e32 v25, v25
	v_add_f32_e32 v2, 1.0, v2
	v_add_f32_e32 v20, 1.0, v20
	v_add_f32_e32 v21, 1.0, v21
	v_add_f32_e32 v22, 1.0, v22
	v_add_f32_e32 v24, 1.0, v24
	v_add_f32_e32 v26, 1.0, v26
	v_add_f32_e32 v23, 1.0, v23
	v_add_f32_e32 v25, 1.0, v25
	v_rcp_f32_e32 v2, v2
	v_rcp_f32_e32 v20, v20
	v_rcp_f32_e32 v21, v21
	v_rcp_f32_e32 v22, v22
	v_rcp_f32_e32 v24, v24
	v_rcp_f32_e32 v26, v26
	v_rcp_f32_e32 v23, v23
	v_rcp_f32_e32 v25, v25
	v_mul_f32_e32 v2, v15, v2
	v_mul_f32_e32 v9, v9, v20
	v_mul_f32_e32 v15, v17, v21
	v_mul_f32_e32 v11, v11, v22
	v_mul_f32_e32 v5, v5, v24
	v_mul_f32_e32 v7, v7, v26
	v_mul_f32_e32 v17, v19, v23
	v_mul_f32_e32 v13, v13, v25
	v_mul_f32_e32 v2, v14, v2
	v_mul_f32_e32 v8, v8, v9
	v_mul_f32_e32 v9, v16, v15
	v_mul_f32_e32 v10, v10, v11
	v_mul_f32_e32 v14, v4, v5
	v_mul_f32_e32 v7, v6, v7
	v_cvt_pk_bf16_f32 v4, v2, v8
	v_cvt_pk_bf16_f32 v5, v9, v10
	v_mul_f32_e32 v11, v18, v17
	v_mul_f32_e32 v12, v12, v13
	v_cvt_pk_bf16_f32 v6, v11, v14
	v_cvt_pk_bf16_f32 v7, v12, v7
	global_store_dwordx2 v[0:1], v[4:5], off
	global_store_dwordx2 v[0:1], v[6:7], off offset:32
	s_barrier
	s_cbranch_scc0 .LBB0_108

; __device__ __forceinline__ void gemm_mainloop_d(const bf16_t* __restrict__ Ap, int lda, const bf16_t* __restrict__ Bt, int K,
;                                                 int m0, int n0, f32x4 (&acc)[4][4], char* lds) {
;     ...
;   auto dma = [&](int kt, int st) {
;     char* la = lds + st * 32768; char* lb = la + 16384;
; #pragma unroll
;     for (int i = 0; i < 4; i++) {
;       const int row = i * 32 + lrow; const int c = cph ^ ((row >> 1) & 7);
;       __builtin_amdgcn_global_load_lds((const unsigned*)(Ap + (size_t)(m0 + row) * lda + kt * 64 + c * 8), (__attribute__((address_space(3))) unsigned*)(la + i * 4096 + tid * 16), 16, 0, 0);
;       __builtin_amdgcn_global_load_lds((const unsigned*)(Bt + (size_t)(n0 + row) * K + kt * 64 + c * 8), (__attribute__((address_space(3))) unsigned*)(lb + i * 4096 + tid * 16), 16, 0, 0);
;     }
;   };
;   dma(0, 0);
;   asm volatile("s_waitcnt vmcnt(0)" ::: "memory"); __builtin_amdgcn_s_barrier(); asm volatile("" ::: "memory");
;   for (int kt = 0; kt < nk; kt++) {
;     const int st = kt & 1;
;     if (kt + 1 < nk) dma(kt + 1, st ^ 1);
;     const char* la = lds + st * 32768; const char* lb = la + 16384;
;     bf16x8 af[2][4], bfv[2][4];
; #pragma unroll
;     for (int kc = 0; kc < 2; kc++) {
; #pragma unroll
;       for (int m = 0; m < 4; m++) { const int row = wr * 64 + m * 16 + fr; af[kc][m] = *(const bf16x8*)(la + (row * 8 + ((kc * 4 + fq) ^ ((row >> 1) & 7))) * 16); }
; #pragma unroll
;       for (int n = 0; n < 4; n++) { const int row = wc * 64 + n * 16 + fr; bfv[kc][n] = *(const bf16x8*)(lb + (row * 8 + ((kc * 4 + fq) ^ ((row >> 1) & 7))) * 16); }
;     }
;     __builtin_amdgcn_s_setprio(1);
; #pragma unroll
;     for (int kc = 0; kc < 2; kc++)
; #pragma unroll
;       for (int m = 0; m < 4; m++)
; #pragma unroll
;         for (int n = 0; n < 4; n++) acc[m][n] = __builtin_amdgcn_mfma_f32_16x16x32_bf16(bfv[kc][n], af[kc][m], acc[m][n], 0, 0, 0);
;     __builtin_amdgcn_s_setprio(0);
;     asm volatile("s_waitcnt vmcnt(0) lgkmcnt(0)" ::: "memory"); __builtin_amdgcn_s_barrier(); asm volatile("" ::: "memory");
;   }
.LBB0_126:
	s_setprio 3
	s_and_b32 s37, s34, 0x8000
	s_xor_b32 s43, s37, 0x8000
	s_add_i32 s43, s43, vcc_hi
	s_mov_b32 m0, s43
	s_add_i32 vcc_lo, s43, 0x4000
	global_load_lds_dwordx4 v150, s[46:47]
	s_mov_b32 m0, vcc_lo
	s_add_i32 vcc_lo, s43, 0x1000
	global_load_lds_dwordx4 v151, s[46:47]
	s_mov_b32 m0, vcc_lo
	s_add_i32 vcc_lo, s43, 0x5000
	global_load_lds_dwordx4 v152, s[46:47]
	s_mov_b32 m0, vcc_lo
	s_add_i32 vcc_lo, s43, 0x2000
	global_load_lds_dwordx4 v153, s[46:47]
	s_mov_b32 m0, vcc_lo
	s_add_i32 vcc_lo, s43, 0x6000
	global_load_lds_dwordx4 v154, s[46:47]
	s_mov_b32 m0, vcc_lo
	s_add_i32 vcc_lo, s43, 0x3000
	global_load_lds_dwordx4 v155, s[46:47]
	s_mov_b32 m0, vcc_lo
	s_add_i32 vcc_lo, s43, 0x7000
	global_load_lds_dwordx4 v156, s[46:47]
	s_mov_b32 m0, vcc_lo
	s_nop 0
	global_load_lds_dwordx4 v157, s[46:47]
	s_setprio 0
	v_add_u32_e32 v150, 0x80, v150
	v_add_u32_e32 v151, 0x80, v151
	v_add_u32_e32 v152, 0x80, v152
	v_add_u32_e32 v153, 0x80, v153
	v_add_u32_e32 v154, 0x80, v154
	v_add_u32_e32 v155, 0x80, v155
	v_add_u32_e32 v156, 0x80, v156
	v_add_u32_e32 v157, 0x80, v157
	v_add_u32_e32 v98, s37, v85
	v_add_u32_e32 v114, s37, v84
	v_add_u32_e32 v130, s37, v83
	v_add_u32_e32 v146, s37, v2
	ds_read_b128 v[86:89], v98
	ds_read_b128 v[90:93], v98 offset:2048
	ds_read_b128 v[94:97], v98 offset:4096
	ds_read_b128 v[98:101], v98 offset:6144
	ds_read_b128 v[102:105], v114 offset:16384
	ds_read_b128 v[106:109], v114 offset:18432
	ds_read_b128 v[110:113], v114 offset:20480
	ds_read_b128 v[114:117], v114 offset:22528
	ds_read_b128 v[118:121], v130
	ds_read_b128 v[122:125], v130 offset:2048
	ds_read_b128 v[126:129], v130 offset:4096
	ds_read_b128 v[130:133], v130 offset:6144
	ds_read_b128 v[134:137], v146 offset:16384
	ds_read_b128 v[138:141], v146 offset:18432
	ds_read_b128 v[142:145], v146 offset:20480
	ds_read_b128 v[146:149], v146 offset:22528
	s_setprio 1
	s_waitcnt lgkmcnt(0)
	v_mfma_f32_16x16x32_bf16 v[64:67], v[102:105], v[86:89], v[64:67]
	v_mfma_f32_16x16x32_bf16 v[60:63], v[106:109], v[86:89], v[60:63]
	v_mfma_f32_16x16x32_bf16 v[56:59], v[110:113], v[86:89], v[56:59]
	v_mfma_f32_16x16x32_bf16 v[52:55], v[114:117], v[86:89], v[52:55]
	v_mfma_f32_16x16x32_bf16 v[48:51], v[102:105], v[90:93], v[48:51]
	v_mfma_f32_16x16x32_bf16 v[44:47], v[106:109], v[90:93], v[44:47]
	v_mfma_f32_16x16x32_bf16 v[40:43], v[110:113], v[90:93], v[40:43]
	v_mfma_f32_16x16x32_bf16 v[36:39], v[114:117], v[90:93], v[36:39]
	v_mfma_f32_16x16x32_bf16 v[32:35], v[102:105], v[94:97], v[32:35]
	v_mfma_f32_16x16x32_bf16 v[28:31], v[106:109], v[94:97], v[28:31]
	v_mfma_f32_16x16x32_bf16 v[24:27], v[110:113], v[94:97], v[24:27]
	v_mfma_f32_16x16x32_bf16 v[20:23], v[114:117], v[94:97], v[20:23]
	v_mfma_f32_16x16x32_bf16 v[16:19], v[102:105], v[98:101], v[16:19]
	v_mfma_f32_16x16x32_bf16 v[12:15], v[106:109], v[98:101], v[12:15]
	v_mfma_f32_16x16x32_bf16 v[8:11], v[110:113], v[98:101], v[8:11]
	v_mfma_f32_16x16x32_bf16 v[4:7], v[114:117], v[98:101], v[4:7]
	v_mfma_f32_16x16x32_bf16 v[64:67], v[134:137], v[118:121], v[64:67]
	v_mfma_f32_16x16x32_bf16 v[60:63], v[138:141], v[118:121], v[60:63]
	v_mfma_f32_16x16x32_bf16 v[56:59], v[142:145], v[118:121], v[56:59]
	v_mfma_f32_16x16x32_bf16 v[52:55], v[146:149], v[118:121], v[52:55]
	v_mfma_f32_16x16x32_bf16 v[48:51], v[134:137], v[122:125], v[48:51]
	v_mfma_f32_16x16x32_bf16 v[44:47], v[138:141], v[122:125], v[44:47]
	v_mfma_f32_16x16x32_bf16 v[40:43], v[142:145], v[122:125], v[40:43]
	v_mfma_f32_16x16x32_bf16 v[36:39], v[146:149], v[122:125], v[36:39]
	v_mfma_f32_16x16x32_bf16 v[32:35], v[134:137], v[126:129], v[32:35]
	v_mfma_f32_16x16x32_bf16 v[28:31], v[138:141], v[126:129], v[28:31]
	v_mfma_f32_16x16x32_bf16 v[24:27], v[142:145], v[126:129], v[24:27]
	v_mfma_f32_16x16x32_bf16 v[20:23], v[146:149], v[126:129], v[20:23]
	v_mfma_f32_16x16x32_bf16 v[16:19], v[134:137], v[130:133], v[16:19]
	v_mfma_f32_16x16x32_bf16 v[12:15], v[138:141], v[130:133], v[12:15]
	v_mfma_f32_16x16x32_bf16 v[8:11], v[142:145], v[130:133], v[8:11]
	v_mfma_f32_16x16x32_bf16 v[4:7], v[146:149], v[130:133], v[4:7]
	s_setprio 0
	s_waitcnt vmcnt(0) lgkmcnt(0)
	s_barrier
	s_add_u32 s30, s30, 0x80
	s_addc_u32 s31, s31, 0
	s_add_i32 s34, s34, 0x8000
	s_cmpk_eq_i32 s30, 0x780
	s_cbranch_scc0 .LBB0_126
; __device__ __forceinline__ void gemm_mainloop_d(const bf16_t* __restrict__ Ap, int lda, const bf16_t* __restrict__ Bt, int K,
;                                                 int m0, int n0, f32x4 (&acc)[4][4], char* lds) {
;     ...
;     const char* la = lds + st * 32768; const char* lb = la + 16384;
;     bf16x8 af[2][4], bfv[2][4];
; #pragma unroll
;     for (int kc = 0; kc < 2; kc++) {
; #pragma unroll
;       for (int m = 0; m < 4; m++) { const int row = wr * 64 + m * 16 + fr; af[kc][m] = *(const bf16x8*)(la + (row * 8 + ((kc * 4 + fq) ^ ((row >> 1) & 7))) * 16); }
; #pragma unroll
;       for (int n = 0; n < 4; n++) { const int row = wc * 64 + n * 16 + fr; bfv[kc][n] = *(const bf16x8*)(lb + (row * 8 + ((kc * 4 + fq) ^ ((row >> 1) & 7))) * 16); }
;     }
;     __builtin_amdgcn_s_setprio(1);
; #pragma unroll
;     for (int kc = 0; kc < 2; kc++)
; #pragma unroll
;       for (int m = 0; m < 4; m++)
; #pragma unroll
;         for (int n = 0; n < 4; n++) acc[m][n] = __builtin_amdgcn_mfma_f32_16x16x32_bf16(bfv[kc][n], af[kc][m], acc[m][n], 0, 0, 0);
;     __builtin_amdgcn_s_setprio(0);
;     asm volatile("s_waitcnt vmcnt(0) lgkmcnt(0)" ::: "memory"); __builtin_amdgcn_s_barrier(); asm volatile("" ::: "memory");
;   }
	v_add_u32_e32 v0, 0, v85
	ds_read_b128 v[68:71], v0 offset:32768
	ds_read_b128 v[72:75], v0 offset:34816
	ds_read_b128 v[76:79], v0 offset:36864
	ds_read_b128 v[86:89], v0 offset:38912
	v_add_u32_e32 v0, 0, v84
	ds_read_b128 v[90:93], v0 offset:49152
	ds_read_b128 v[94:97], v0 offset:51200
	ds_read_b128 v[98:101], v0 offset:53248
	ds_read_b128 v[102:105], v0 offset:55296
	v_add_u32_e32 v0, 0, v83
	s_add_u32 s30, s46, s35
	ds_read_b128 v[80:83], v0 offset:32768
	ds_read_b128 v[106:109], v0 offset:34816
	ds_read_b128 v[110:113], v0 offset:36864
	ds_read_b128 v[114:117], v0 offset:38912
	v_add_u32_e32 v0, 0, v2
	s_addc_u32 s31, s47, 0
	ds_read_b128 v[118:121], v0 offset:49152
	ds_read_b128 v[122:125], v0 offset:51200
	ds_read_b128 v[126:129], v0 offset:53248
	ds_read_b128 v[130:133], v0 offset:55296
	s_add_u32 s36, s46, s36
	s_addc_u32 s37, s47, 0
	s_add_u32 s34, s30, 0x65a8000
	s_addc_u32 s35, s31, 0
	s_add_u32 s30, s36, 0xff9c000
	s_addc_u32 s31, s37, 0
	s_setprio 1
	s_waitcnt lgkmcnt(0)
	v_mfma_f32_16x16x32_bf16 v[56:59], v[98:101], v[68:71], v[56:59]
	v_mfma_f32_16x16x32_bf16 v[48:51], v[90:93], v[72:75], v[48:51]
	v_mfma_f32_16x16x32_bf16 v[44:47], v[94:97], v[72:75], v[44:47]
	v_mfma_f32_16x16x32_bf16 v[40:43], v[98:101], v[72:75], v[40:43]
	v_mfma_f32_16x16x32_bf16 v[36:39], v[102:105], v[72:75], v[36:39]
	v_mfma_f32_16x16x32_bf16 v[32:35], v[90:93], v[76:79], v[32:35]
	v_mfma_f32_16x16x32_bf16 v[28:31], v[94:97], v[76:79], v[28:31]
	v_mfma_f32_16x16x32_bf16 v[24:27], v[98:101], v[76:79], v[24:27]
	v_mfma_f32_16x16x32_bf16 v[20:23], v[102:105], v[76:79], v[20:23]
	v_mfma_f32_16x16x32_bf16 v[16:19], v[90:93], v[86:89], v[16:19]
	v_mfma_f32_16x16x32_bf16 v[12:15], v[94:97], v[86:89], v[12:15]
	v_mfma_f32_16x16x32_bf16 v[8:11], v[98:101], v[86:89], v[8:11]
	v_mfma_f32_16x16x32_bf16 v[4:7], v[102:105], v[86:89], v[4:7]
	v_mfma_f32_16x16x32_bf16 v[64:67], v[90:93], v[68:71], v[64:67]
	v_mfma_f32_16x16x32_bf16 v[60:63], v[94:97], v[68:71], v[60:63]
	v_mfma_f32_16x16x32_bf16 v[52:55], v[102:105], v[68:71], v[52:55]
	v_mfma_f32_16x16x32_bf16 v[56:59], v[126:129], v[80:83], v[56:59]
	v_mfma_f32_16x16x32_bf16 v[48:51], v[118:121], v[106:109], v[48:51]
	v_mfma_f32_16x16x32_bf16 v[44:47], v[122:125], v[106:109], v[44:47]
	v_mfma_f32_16x16x32_bf16 v[40:43], v[126:129], v[106:109], v[40:43]
	v_mfma_f32_16x16x32_bf16 v[36:39], v[130:133], v[106:109], v[36:39]
	v_mfma_f32_16x16x32_bf16 v[32:35], v[118:121], v[110:113], v[32:35]
	v_mfma_f32_16x16x32_bf16 v[28:31], v[122:125], v[110:113], v[28:31]
	v_mfma_f32_16x16x32_bf16 v[24:27], v[126:129], v[110:113], v[24:27]
	v_mfma_f32_16x16x32_bf16 v[20:23], v[130:133], v[110:113], v[20:23]
	v_mfma_f32_16x16x32_bf16 v[16:19], v[118:121], v[114:117], v[16:19]
	v_mfma_f32_16x16x32_bf16 v[12:15], v[122:125], v[114:117], v[12:15]
	v_mfma_f32_16x16x32_bf16 v[8:11], v[126:129], v[114:117], v[8:11]
	v_mfma_f32_16x16x32_bf16 v[4:7], v[130:133], v[114:117], v[4:7]
	v_mfma_f32_16x16x32_bf16 v[64:67], v[118:121], v[80:83], v[64:67]
	v_mfma_f32_16x16x32_bf16 v[60:63], v[122:125], v[80:83], v[60:63]
	v_mfma_f32_16x16x32_bf16 v[68:71], v[130:133], v[80:83], v[52:55]
	s_setprio 0
	v_mov_b32_e32 v0, v198
	s_waitcnt vmcnt(0) lgkmcnt(0)
	s_barrier
; __device__ __forceinline__ unsigned pk2(float lo, float hi) { unsigned r; asm("v_cvt_pk_bf16_f32 %0, %1, %2" : "=v"(r) : "v"(lo), "v"(hi)); return r; }
; __device__ __forceinline__ float bflo(unsigned u) { return __uint_as_float(u << 16); }
; __device__ __forceinline__ float bfhi(unsigned u) { return __uint_as_float(u & 0xffff0000u); }
; __device__ __forceinline__ void gemm_RES(const bf16_t* A, int K, const bf16_t* Bt, const float* xin, float* xout, bf16_t* xb, float* rss, int item, char* lds) {
;     ...
; #pragma unroll
;   for (int m = 0; m < 4; m++) {
;     const int rowg = m0 + wr * 64 + m * 16 + fr;
;     const size_t ro = (size_t)rowg * DM;
;     float sq = 0.f;
; #pragma unroll
;     for (int n = 0; n < 4; n++) {
;       const int col = n0 + wc * 64 + n * 16 + fq * 4;
;       f32x4 xv = *(const f32x4*)(xin + ro + col);
;       const f32x4 xn = xv + acc[m][n];
;       *(f32x4*)(xout + ro + col) = xn;
;       u32x2 w; w[0] = pk2(xn[0], xn[1]); w[1] = pk2(xn[2], xn[3]); *(u32x2*)(xb + ro + col) = w;
;       const float b0 = bflo(w[0]), b1 = bfhi(w[0]), b2 = bflo(w[1]), b3 = bfhi(w[1]);
;       sq += b0 * b0 + b1 * b1 + b2 * b2 + b3 * b3;
;     }
;     sq += __shfl_xor(sq, 16); sq += __shfl_xor(sq, 32);
;     if (fq == 0) unsafeAtomicAdd(rss + rowg, sq);
;   }
	v_readlane_b32 s4, v252, 35
	v_ashrrev_i32_e32 v2, 1, v0
	v_and_b32_e32 v2, 0xffffffc0, v2
	v_add_u32_e32 v2, s3, v2
	v_bfe_u32 v82, v0, 4, 2
	v_and_or_b32 v52, v0, 15, v2
	v_and_b32_e32 v1, 64, v0
	v_lshlrev_b32_e32 v0, 2, v82
	v_ashrrev_i32_e32 v53, 31, v52
	v_or3_b32 v78, v0, v1, s2
	v_lshlrev_b64 v[54:55], 12, v[52:53]
	v_lshl_add_u64 v[0:1], s[26:27], 0, v[54:55]
	v_lshlrev_b32_e32 v2, 2, v78
	v_lshl_add_u64 v[76:77], v[0:1], 0, v[2:3]
	global_load_dwordx4 v[72:75], v[76:77], off
	v_lshlrev_b32_e32 v0, 1, v78
	v_lshlrev_b64 v[78:79], 11, v[52:53]
	v_readlane_b32 s18, v252, 49
	v_readlane_b32 s19, v252, 50
	v_mov_b32_e32 v1, v3
	v_lshl_add_u64 v[78:79], s[34:35], 0, v[78:79]
	v_lshl_add_u64 v[54:55], s[18:19], 0, v[54:55]
	v_lshl_add_u64 v[80:81], v[54:55], 0, v[2:3]
	v_lshl_add_u64 v[78:79], v[78:79], 0, v[0:1]
	v_readlane_b32 s5, v252, 36
	v_readlane_b32 s6, v252, 37
	v_readlane_b32 s7, v252, 38
	v_readlane_b32 s8, v252, 39
	v_readlane_b32 s9, v252, 40
	v_readlane_b32 s10, v252, 41
	v_readlane_b32 s11, v252, 42
	v_readlane_b32 s12, v252, 43
	v_readlane_b32 s13, v252, 44
	v_readlane_b32 s14, v252, 45
	v_readlane_b32 s15, v252, 46
	v_readlane_b32 s16, v252, 47
	v_readlane_b32 s17, v252, 48
	s_waitcnt vmcnt(0)
	v_pk_add_f32 v[66:67], v[66:67], v[74:75]
	v_pk_add_f32 v[64:65], v[64:65], v[72:73]
	global_store_dwordx4 v[80:81], v[64:67], off
	v_cvt_pk_bf16_f32 v54, v64, v65
	v_cvt_pk_bf16_f32 v55, v66, v67
	global_store_dwordx2 v[78:79], v[54:55], off
	global_load_dwordx4 v[64:67], v[76:77], off offset:64
	s_waitcnt vmcnt(0)
	v_pk_add_f32 v[62:63], v[62:63], v[66:67]
	v_pk_add_f32 v[60:61], v[60:61], v[64:65]
	global_store_dwordx4 v[80:81], v[60:63], off offset:64
	v_cvt_pk_bf16_f32 v64, v60, v61
	v_cvt_pk_bf16_f32 v65, v62, v63
	global_store_dwordx2 v[78:79], v[64:65], off offset:32
	global_load_dwordx4 v[60:63], v[76:77], off offset:128
	v_lshlrev_b32_e32 v66, 16, v54
	v_and_b32_e32 v54, 0xffff0000, v54
	v_mul_f32_e32 v54, v54, v54
	v_lshlrev_b32_e32 v67, 16, v55
	v_fmac_f32_e32 v54, v66, v66
	v_and_b32_e32 v55, 0xffff0000, v55
	v_fmac_f32_e32 v54, v67, v67
	v_fmac_f32_e32 v54, v55, v55
	v_lshlrev_b32_e32 v55, 16, v64
	v_and_b32_e32 v64, 0xffff0000, v64
	v_mul_f32_e32 v64, v64, v64
	v_lshlrev_b32_e32 v66, 16, v65
	v_fmac_f32_e32 v64, v55, v55
	v_and_b32_e32 v65, 0xffff0000, v65
	v_fmac_f32_e32 v64, v66, v66
	v_fmac_f32_e32 v64, v65, v65
	v_add_f32_e32 v54, v54, v64
	s_waitcnt vmcnt(0)
	v_pk_add_f32 v[58:59], v[58:59], v[62:63]
	v_pk_add_f32 v[56:57], v[56:57], v[60:61]
	global_store_dwordx4 v[80:81], v[56:59], off offset:128
	v_cvt_pk_bf16_f32 v62, v56, v57
	v_cvt_pk_bf16_f32 v63, v58, v59
	global_store_dwordx2 v[78:79], v[62:63], off offset:64
	global_load_dwordx4 v[58:61], v[76:77], off offset:192
	v_lshlrev_b32_e32 v55, 16, v62
	v_and_b32_e32 v62, 0xffff0000, v62
	v_mul_f32_e32 v62, v62, v62
	v_lshlrev_b32_e32 v64, 16, v63
	v_fmac_f32_e32 v62, v55, v55
	v_and_b32_e32 v63, 0xffff0000, v63
	v_fmac_f32_e32 v62, v64, v64
	v_fmac_f32_e32 v62, v63, v63
	v_add_f32_e32 v54, v54, v62
	v_and_b32_e32 v57, 64, v218
	v_xor_b32_e32 v56, 16, v218
	v_add_u32_e32 v57, 64, v57
	v_cmp_lt_i32_e32 vcc, v56, v57
	s_waitcnt vmcnt(0)
	v_pk_add_f32 v[58:59], v[68:69], v[58:59]
	s_nop 0
	v_cvt_pk_bf16_f32 v62, v58, v59
	v_pk_add_f32 v[60:61], v[70:71], v[60:61]
	v_and_b32_e32 v64, 0xffff0000, v62
	v_lshlrev_b32_e32 v55, 16, v62
	v_mul_f32_e32 v64, v64, v64
	v_cvt_pk_bf16_f32 v63, v60, v61
	v_fmac_f32_e32 v64, v55, v55
	v_lshlrev_b32_e32 v65, 16, v63
	v_and_b32_e32 v66, 0xffff0000, v63
	v_fmac_f32_e32 v64, v65, v65
	v_cndmask_b32_e32 v56, v218, v56, vcc
	v_fmac_f32_e32 v64, v66, v66
	v_lshlrev_b32_e32 v56, 2, v56
	v_add_f32_e32 v54, v54, v64
	ds_bpermute_b32 v55, v56, v54
	v_xor_b32_e32 v64, 32, v218
	v_cmp_lt_i32_e32 vcc, v64, v57
	global_store_dwordx4 v[80:81], v[58:61], off offset:192
	global_store_dwordx2 v[78:79], v[62:63], off offset:96
	v_cndmask_b32_e32 v57, v218, v64, vcc
	s_waitcnt lgkmcnt(0)
	v_add_f32_e32 v54, v54, v55
	v_lshlrev_b32_e32 v57, 2, v57
	ds_bpermute_b32 v55, v57, v54
	v_cmp_eq_u32_e32 vcc, 0, v82
	s_and_saveexec_b64 s[36:37], vcc
	s_cbranch_execz .LBB0_129
	v_lshl_add_u64 v[58:59], v[52:53], 2, s[30:31]
	s_waitcnt lgkmcnt(0)
	v_add_f32_e32 v53, v54, v55
	global_atomic_add_f32 v[58:59], v53, off

; __device__ __forceinline__ void gemm_mainloop_d(const bf16_t* __restrict__ Ap, int lda, const bf16_t* __restrict__ Bt, int K,
;                                                 int m0, int n0, f32x4 (&acc)[4][4], char* lds) {
;     ...
;   auto dma = [&](int kt, int st) {
;     char* la = lds + st * 32768; char* lb = la + 16384;
; #pragma unroll
;     for (int i = 0; i < 4; i++) {
;       const int row = i * 32 + lrow; const int c = cph ^ ((row >> 1) & 7);
;       __builtin_amdgcn_global_load_lds((const unsigned*)(Ap + (size_t)(m0 + row) * lda + kt * 64 + c * 8), (__attribute__((address_space(3))) unsigned*)(la + i * 4096 + tid * 16), 16, 0, 0);
;       __builtin_amdgcn_global_load_lds((const unsigned*)(Bt + (size_t)(n0 + row) * K + kt * 64 + c * 8), (__attribute__((address_space(3))) unsigned*)(lb + i * 4096 + tid * 16), 16, 0, 0);
;     }
;   };
;   dma(0, 0);
;   asm volatile("s_waitcnt vmcnt(0)" ::: "memory"); __builtin_amdgcn_s_barrier(); asm volatile("" ::: "memory");
;   for (int kt = 0; kt < nk; kt++) {
;     const int st = kt & 1;
;     if (kt + 1 < nk) dma(kt + 1, st ^ 1);
;     const char* la = lds + st * 32768; const char* lb = la + 16384;
;     bf16x8 af[2][4], bfv[2][4];
; #pragma unroll
;     for (int kc = 0; kc < 2; kc++) {
; #pragma unroll
;       for (int m = 0; m < 4; m++) { const int row = wr * 64 + m * 16 + fr; af[kc][m] = *(const bf16x8*)(la + (row * 8 + ((kc * 4 + fq) ^ ((row >> 1) & 7))) * 16); }
; #pragma unroll
;       for (int n = 0; n < 4; n++) { const int row = wc * 64 + n * 16 + fr; bfv[kc][n] = *(const bf16x8*)(lb + (row * 8 + ((kc * 4 + fq) ^ ((row >> 1) & 7))) * 16); }
;     }
;     __builtin_amdgcn_s_setprio(1);
; #pragma unroll
;     for (int kc = 0; kc < 2; kc++)
; #pragma unroll
;       for (int m = 0; m < 4; m++)
; #pragma unroll
;         for (int n = 0; n < 4; n++) acc[m][n] = __builtin_amdgcn_mfma_f32_16x16x32_bf16(bfv[kc][n], af[kc][m], acc[m][n], 0, 0, 0);
;     __builtin_amdgcn_s_setprio(0);
;     asm volatile("s_waitcnt vmcnt(0) lgkmcnt(0)" ::: "memory"); __builtin_amdgcn_s_barrier(); asm volatile("" ::: "memory");
;   }
.LBB0_657:
	s_setprio 3
	s_and_b32 s28, s25, 0x8000
	s_xor_b32 s29, s28, 0x8000
	s_add_i32 s29, s29, vcc_hi
	s_mov_b32 m0, s29
	s_add_i32 vcc_lo, s29, 0x4000
	global_load_lds_dwordx4 v150, s[46:47]
	s_mov_b32 m0, vcc_lo
	s_add_i32 vcc_lo, s29, 0x1000
	global_load_lds_dwordx4 v151, s[46:47]
	s_mov_b32 m0, vcc_lo
	s_add_i32 vcc_lo, s29, 0x5000
	global_load_lds_dwordx4 v152, s[46:47]
	s_mov_b32 m0, vcc_lo
	s_add_i32 vcc_lo, s29, 0x2000
	global_load_lds_dwordx4 v153, s[46:47]
	s_mov_b32 m0, vcc_lo
	s_add_i32 vcc_lo, s29, 0x6000
	global_load_lds_dwordx4 v154, s[46:47]
	s_mov_b32 m0, vcc_lo
	s_add_i32 vcc_lo, s29, 0x3000
	global_load_lds_dwordx4 v155, s[46:47]
	s_mov_b32 m0, vcc_lo
	s_add_i32 vcc_lo, s29, 0x7000
	global_load_lds_dwordx4 v156, s[46:47]
	s_mov_b32 m0, vcc_lo
	s_nop 0
	global_load_lds_dwordx4 v157, s[46:47]
	s_setprio 0
	v_add_u32_e32 v150, 0x80, v150
	v_add_u32_e32 v151, 0x80, v151
	v_add_u32_e32 v152, 0x80, v152
	v_add_u32_e32 v153, 0x80, v153
	v_add_u32_e32 v154, 0x80, v154
	v_add_u32_e32 v155, 0x80, v155
	v_add_u32_e32 v156, 0x80, v156
	v_add_u32_e32 v157, 0x80, v157
	v_add_u32_e32 v98, s28, v85
	v_add_u32_e32 v114, s28, v84
	v_add_u32_e32 v130, s28, v83
	v_add_u32_e32 v146, s28, v2
	ds_read_b128 v[86:89], v98
	ds_read_b128 v[90:93], v98 offset:2048
	ds_read_b128 v[94:97], v98 offset:4096
	ds_read_b128 v[98:101], v98 offset:6144
	ds_read_b128 v[102:105], v114 offset:16384
	ds_read_b128 v[106:109], v114 offset:18432
	ds_read_b128 v[110:113], v114 offset:20480
	ds_read_b128 v[114:117], v114 offset:22528
	ds_read_b128 v[118:121], v130
	ds_read_b128 v[122:125], v130 offset:2048
	ds_read_b128 v[126:129], v130 offset:4096
	ds_read_b128 v[130:133], v130 offset:6144
	ds_read_b128 v[134:137], v146 offset:16384
	ds_read_b128 v[138:141], v146 offset:18432
	ds_read_b128 v[142:145], v146 offset:20480
	ds_read_b128 v[146:149], v146 offset:22528
	s_setprio 1
	s_waitcnt lgkmcnt(0)
	v_mfma_f32_16x16x32_bf16 v[64:67], v[102:105], v[86:89], v[64:67]
	v_mfma_f32_16x16x32_bf16 v[60:63], v[106:109], v[86:89], v[60:63]
	v_mfma_f32_16x16x32_bf16 v[56:59], v[110:113], v[86:89], v[56:59]
	v_mfma_f32_16x16x32_bf16 v[52:55], v[114:117], v[86:89], v[52:55]
	v_mfma_f32_16x16x32_bf16 v[48:51], v[102:105], v[90:93], v[48:51]
	v_mfma_f32_16x16x32_bf16 v[44:47], v[106:109], v[90:93], v[44:47]
	v_mfma_f32_16x16x32_bf16 v[40:43], v[110:113], v[90:93], v[40:43]
	v_mfma_f32_16x16x32_bf16 v[36:39], v[114:117], v[90:93], v[36:39]
	v_mfma_f32_16x16x32_bf16 v[32:35], v[102:105], v[94:97], v[32:35]
	v_mfma_f32_16x16x32_bf16 v[28:31], v[106:109], v[94:97], v[28:31]
	v_mfma_f32_16x16x32_bf16 v[24:27], v[110:113], v[94:97], v[24:27]
	v_mfma_f32_16x16x32_bf16 v[20:23], v[114:117], v[94:97], v[20:23]
	v_mfma_f32_16x16x32_bf16 v[16:19], v[102:105], v[98:101], v[16:19]
	v_mfma_f32_16x16x32_bf16 v[12:15], v[106:109], v[98:101], v[12:15]
	v_mfma_f32_16x16x32_bf16 v[8:11], v[110:113], v[98:101], v[8:11]
	v_mfma_f32_16x16x32_bf16 v[4:7], v[114:117], v[98:101], v[4:7]
	v_mfma_f32_16x16x32_bf16 v[64:67], v[134:137], v[118:121], v[64:67]
	v_mfma_f32_16x16x32_bf16 v[60:63], v[138:141], v[118:121], v[60:63]
	v_mfma_f32_16x16x32_bf16 v[56:59], v[142:145], v[118:121], v[56:59]
	v_mfma_f32_16x16x32_bf16 v[52:55], v[146:149], v[118:121], v[52:55]
	v_mfma_f32_16x16x32_bf16 v[48:51], v[134:137], v[122:125], v[48:51]
	v_mfma_f32_16x16x32_bf16 v[44:47], v[138:141], v[122:125], v[44:47]
	v_mfma_f32_16x16x32_bf16 v[40:43], v[142:145], v[122:125], v[40:43]
	v_mfma_f32_16x16x32_bf16 v[36:39], v[146:149], v[122:125], v[36:39]
	v_mfma_f32_16x16x32_bf16 v[32:35], v[134:137], v[126:129], v[32:35]
	v_mfma_f32_16x16x32_bf16 v[28:31], v[138:141], v[126:129], v[28:31]
	v_mfma_f32_16x16x32_bf16 v[24:27], v[142:145], v[126:129], v[24:27]
	v_mfma_f32_16x16x32_bf16 v[20:23], v[146:149], v[126:129], v[20:23]
	v_mfma_f32_16x16x32_bf16 v[16:19], v[134:137], v[130:133], v[16:19]
	v_mfma_f32_16x16x32_bf16 v[12:15], v[138:141], v[130:133], v[12:15]
	v_mfma_f32_16x16x32_bf16 v[8:11], v[142:145], v[130:133], v[8:11]
	v_mfma_f32_16x16x32_bf16 v[4:7], v[146:149], v[130:133], v[4:7]
	s_setprio 0
	s_waitcnt vmcnt(0) lgkmcnt(0)
	s_barrier
	s_add_u32 s26, s26, 0x80
	s_addc_u32 s27, s27, 0
	s_add_i32 s25, s25, 0x8000
	s_cmpk_eq_i32 s26, 0x780
	s_cbranch_scc0 .LBB0_657
; __device__ __forceinline__ unsigned char* WS(const Params& p) { unsigned z = 0; asm volatile("" : "+s"(z)); return p.ws + z; }
; __device__ __forceinline__ unsigned pk2(float lo, float hi) { unsigned r; asm("v_cvt_pk_bf16_f32 %0, %1, %2" : "=v"(r) : "v"(lo), "v"(hi)); return r; }
; __device__ __forceinline__ float bflo(unsigned u) { return __uint_as_float(u << 16); }
; __device__ __forceinline__ void gemm_mainloop_d(const bf16_t* __restrict__ Ap, int lda, const bf16_t* __restrict__ Bt, int K,
;                                                 int m0, int n0, f32x4 (&acc)[4][4], char* lds) {
;     ...
;     const char* la = lds + st * 32768; const char* lb = la + 16384;
;     bf16x8 af[2][4], bfv[2][4];
; #pragma unroll
;     for (int kc = 0; kc < 2; kc++) {
; #pragma unroll
;       for (int m = 0; m < 4; m++) { const int row = wr * 64 + m * 16 + fr; af[kc][m] = *(const bf16x8*)(la + (row * 8 + ((kc * 4 + fq) ^ ((row >> 1) & 7))) * 16); }
; #pragma unroll
;       for (int n = 0; n < 4; n++) { const int row = wc * 64 + n * 16 + fr; bfv[kc][n] = *(const bf16x8*)(lb + (row * 8 + ((kc * 4 + fq) ^ ((row >> 1) & 7))) * 16); }
;     }
;     __builtin_amdgcn_s_setprio(1);
; #pragma unroll
;     for (int kc = 0; kc < 2; kc++)
; #pragma unroll
;       for (int m = 0; m < 4; m++)
; #pragma unroll
;         for (int n = 0; n < 4; n++) acc[m][n] = __builtin_amdgcn_mfma_f32_16x16x32_bf16(bfv[kc][n], af[kc][m], acc[m][n], 0, 0, 0);
;     __builtin_amdgcn_s_setprio(0);
;     asm volatile("s_waitcnt vmcnt(0) lgkmcnt(0)" ::: "memory"); __builtin_amdgcn_s_barrier(); asm volatile("" ::: "memory");
;   }
; __device__ __forceinline__ void gemm_A(const Params& p, int item, char* lds) {
;     ...
;   const float* rssg = (const float*)(WS(p) + OFF_RSS) + m0;
;   bf16_t* P = (bf16_t*)(WS(p) + OFF_P);
; #pragma unroll
;   for (int m = 0; m < 4; m++) {
;     const int rl = wr * 64 + m * 16 + fr; const float r = rsqrtf(rssg[rl] * (1.f / 1024.f) + 1e-6f);
;     float sq = 0.f;
; #pragma unroll
;     for (int n = 0; n < 4; n++) {
;       const int col = n0 + wc * 64 + n * 16 + fq * 4;
;       if (col < PIN) { f32x4 v = acc[m][n] * r; u32x2 w; w[0] = pk2(v[0], v[1]); w[1] = pk2(v[2], v[3]); *(u32x2*)(P + (size_t)(m0 + rl) * PIN + col) = w;
;         const float b0 = bflo(w[0]), b1 = bfhi(w[0]), b2 = bflo(w[1]), b3 = bfhi(w[1]); sq += b0 * b0 + b1 * b1 + b2 * b2 + b3 * b3; }
	v_add_u32_e32 v0, 0, v85
	ds_read_b128 v[68:71], v0 offset:32768
	ds_read_b128 v[72:75], v0 offset:34816
	ds_read_b128 v[76:79], v0 offset:36864
	ds_read_b128 v[86:89], v0 offset:38912
	v_add_u32_e32 v0, 0, v84
	ds_read_b128 v[90:93], v0 offset:49152
	ds_read_b128 v[94:97], v0 offset:51200
	ds_read_b128 v[98:101], v0 offset:53248
	ds_read_b128 v[102:105], v0 offset:55296
	v_add_u32_e32 v0, 0, v83
	ds_read_b128 v[80:83], v0 offset:32768
	ds_read_b128 v[106:109], v0 offset:34816
	ds_read_b128 v[110:113], v0 offset:36864
	ds_read_b128 v[114:117], v0 offset:38912
	v_add_u32_e32 v0, 0, v2
	ds_read_b128 v[118:121], v0 offset:49152
	ds_read_b128 v[122:125], v0 offset:51200
	ds_read_b128 v[126:129], v0 offset:53248
	ds_read_b128 v[130:133], v0 offset:55296
	s_setprio 1
	s_waitcnt lgkmcnt(0)
	v_mfma_f32_16x16x32_bf16 v[64:67], v[90:93], v[68:71], v[64:67]
	v_mfma_f32_16x16x32_bf16 v[60:63], v[94:97], v[68:71], v[60:63]
	v_mfma_f32_16x16x32_bf16 v[56:59], v[98:101], v[68:71], v[56:59]
	v_mfma_f32_16x16x32_bf16 v[52:55], v[102:105], v[68:71], v[52:55]
	v_mfma_f32_16x16x32_bf16 v[48:51], v[90:93], v[72:75], v[48:51]
	v_mfma_f32_16x16x32_bf16 v[44:47], v[94:97], v[72:75], v[44:47]
	v_mfma_f32_16x16x32_bf16 v[40:43], v[98:101], v[72:75], v[40:43]
	v_mfma_f32_16x16x32_bf16 v[36:39], v[102:105], v[72:75], v[36:39]
	v_mfma_f32_16x16x32_bf16 v[32:35], v[90:93], v[76:79], v[32:35]
	v_mfma_f32_16x16x32_bf16 v[28:31], v[94:97], v[76:79], v[28:31]
	v_mfma_f32_16x16x32_bf16 v[24:27], v[98:101], v[76:79], v[24:27]
	v_mfma_f32_16x16x32_bf16 v[20:23], v[102:105], v[76:79], v[20:23]
	v_mfma_f32_16x16x32_bf16 v[16:19], v[90:93], v[86:89], v[16:19]
	v_mfma_f32_16x16x32_bf16 v[12:15], v[94:97], v[86:89], v[12:15]
	v_mfma_f32_16x16x32_bf16 v[8:11], v[98:101], v[86:89], v[8:11]
	v_mfma_f32_16x16x32_bf16 v[4:7], v[102:105], v[86:89], v[4:7]
	v_mfma_f32_16x16x32_bf16 v[64:67], v[118:121], v[80:83], v[64:67]
	v_mfma_f32_16x16x32_bf16 v[60:63], v[122:125], v[80:83], v[60:63]
	v_mfma_f32_16x16x32_bf16 v[56:59], v[126:129], v[80:83], v[56:59]
	v_mfma_f32_16x16x32_bf16 v[52:55], v[130:133], v[80:83], v[52:55]
	v_mfma_f32_16x16x32_bf16 v[48:51], v[118:121], v[106:109], v[48:51]
	v_mfma_f32_16x16x32_bf16 v[44:47], v[122:125], v[106:109], v[44:47]
	v_mfma_f32_16x16x32_bf16 v[40:43], v[126:129], v[106:109], v[40:43]
	v_mfma_f32_16x16x32_bf16 v[36:39], v[130:133], v[106:109], v[36:39]
	v_mfma_f32_16x16x32_bf16 v[32:35], v[118:121], v[110:113], v[32:35]
	v_mfma_f32_16x16x32_bf16 v[28:31], v[122:125], v[110:113], v[28:31]
	v_mfma_f32_16x16x32_bf16 v[24:27], v[126:129], v[110:113], v[24:27]
	v_mfma_f32_16x16x32_bf16 v[20:23], v[130:133], v[110:113], v[20:23]
	v_mfma_f32_16x16x32_bf16 v[16:19], v[118:121], v[114:117], v[16:19]
	v_mfma_f32_16x16x32_bf16 v[12:15], v[122:125], v[114:117], v[12:15]
	v_mfma_f32_16x16x32_bf16 v[8:11], v[126:129], v[114:117], v[8:11]
	v_mfma_f32_16x16x32_bf16 v[4:7], v[130:133], v[114:117], v[4:7]
	s_setprio 0
	v_mov_b32_e32 v2, v198
	s_mov_b32 s25, s89
	s_waitcnt vmcnt(0) lgkmcnt(0)
	s_barrier
	s_add_u32 s28, s46, s25
	s_addc_u32 s29, s47, 0
	s_ashr_i32 s25, s24, 31
	v_and_b32_e32 v0, 15, v2
	s_lshl_b64 s[26:27], s[24:25], 2
	v_ashrrev_i32_e32 v1, 1, v2
	s_movk_i32 s4, 0xffc0
	s_add_u32 s28, s28, s26
	v_and_or_b32 v0, v1, s4, v0
	s_addc_u32 s29, s29, s27
	v_ashrrev_i32_e32 v1, 31, v0
	v_lshl_add_u64 v[70:71], v[0:1], 2, s[28:29]
	s_mov_b32 s28, 0xff8c000
	v_add_co_u32_e32 v68, vcc, s28, v70
	s_mov_b32 s25, s89
	s_nop 0
	v_addc_co_u32_e32 v69, vcc, 0, v71, vcc
	global_load_dword v69, v[68:69], off
	v_and_b32_e32 v68, 64, v2
	v_bfe_u32 v2, v2, 4, 2
	v_lshlrev_b32_e32 v72, 2, v2
	v_or3_b32 v68, v72, v68, s3
	s_add_u32 s3, s46, s25
	s_addc_u32 s25, s47, 0
	s_add_u32 s30, s3, 0x768000
	s_addc_u32 s31, s25, 0
	v_add_u32_e32 v74, s24, v0
	v_mov_b32_e32 v76, 0
	v_cmp_gt_i32_e64 s[34:35], s78, v68
	s_waitcnt vmcnt(0)
	v_fmamk_f32 v69, v69, 0x3a800000, v200
	v_mul_f32_e32 v72, 0x4b800000, v69
	v_cmp_gt_f32_e32 vcc, s83, v69
	s_nop 1
	v_cndmask_b32_e32 v69, v69, v72, vcc
	v_rsq_f32_e32 v69, v69
	v_mov_b64_e32 v[72:73], s[30:31]
	v_mad_i64_i32 v[72:73], s[28:29], v74, s69, v[72:73]
	v_mul_f32_e32 v74, 0x45800000, v69
	v_cndmask_b32_e32 v74, v69, v74, vcc
	v_mov_b32_e32 v75, v74
	v_ashrrev_i32_e32 v69, 31, v68
	s_and_saveexec_b64 s[28:29], s[34:35]
	s_cbranch_execz .LBB0_660
	v_mov_b32_e32 v76, v74
	v_mov_b32_e32 v77, v74
	v_pk_mul_f32 v[66:67], v[66:67], v[76:77]
	v_pk_mul_f32 v[64:65], v[64:65], v[74:75]
	s_nop 0
	v_cvt_pk_bf16_f32 v64, v64, v65
	v_cvt_pk_bf16_f32 v65, v66, v67
	v_lshl_add_u64 v[66:67], v[68:69], 1, v[72:73]
	global_store_dwordx2 v[66:67], v[64:65], off
	v_lshlrev_b32_e32 v66, 16, v64
	v_and_b32_e32 v67, 0xffff0000, v64
	v_pk_mul_f32 v[66:67], v[66:67], v[66:67]
	v_and_b32_e32 v64, 0xffff0000, v65
	v_lshlrev_b32_e32 v65, 16, v65
	v_pk_mul_f32 v[64:65], v[64:65], v[64:65]
	v_add_f32_e32 v66, v66, v67
	v_add_f32_e32 v65, v66, v65
	v_add_f32_e32 v76, v64, v65
